# GEMM K-loops: first iteration after an epilogue uses vmcnt(8+E) so the epilogue stores need not be acked before the first two load segments
# baseline (speedup 1.0000x reference)
;     __host__ __device__ bool next(int i, Unit& u) const { if (!base.next(i >> 1, u)) return false; if (i & 1) { u.pm += 64; u.pn += 8; } return true; }
; #define PG8_STAGE(bufoff, gbase, voff) do { _Pragma("unroll") for (int _i = 0; _i < 2; ++_i) \
;         __builtin_amdgcn_global_load_lds((const unsigned*)((const char*)(gbase) + (voff)[_i]), (PG8_LAS unsigned*)(lds + (bufoff) + ldsw + _i * 8192), 16, 0, 0); } while (0)
; #define PG8_LDA(dst, b, h) do { _Pragma("unroll") for (int m = 0; m < 4; ++m) _Pragma("unroll") for (int k = 0; k < 2; ++k) dst[m][k] = *(const PG8_LAS bf16x8*)(lds + PG8_SA(b, h) + aoff + m * 2048 + k * 1024); } while (0)
; #define PG8_LDB(dst, b, h) do { _Pragma("unroll") for (int n = 0; n < 2; ++n) _Pragma("unroll") for (int k = 0; k < 2; ++k) dst[n][k] = *(const PG8_LAS bf16x8*)(lds + PG8_SB(b, h) + boff + n * 2048 + k * 1024); } while (0)
; #define PG8_SCHED __builtin_amdgcn_sched_barrier(0)
; template <class Epi, class Sched, bool ALIGN_EPI = false, bool SP2 = false>
; __device__ __forceinline__ void gemm_phase(PG8_LAS unsigned char* lds, const Gemm g, const Sched& S, const Epi& E) {
;     ...
;         const bool has_next = S.next(ui + 1, nxt);
;         const char* nA = has_next ? (const char*)g.A + (size_t)nxt.pm * tstep : cA; const char* nB = has_next ? (const char*)g.Bt + (size_t)nxt.pn * tstep : cB;
;         for (int t = 0; t < nt; t += 2) {
;             const bool last = (t == nt - 2);
;             const char* a1 = cA + (size_t)(t + 1) * kstep;
;             const char* a2 = last ? nA : cA + (size_t)(t + 2) * kstep; const char* b2 = last ? nB : cB + (size_t)(t + 2) * kstep;
;             const char* a3 = a2 + kstep; const char* b3 = b2 + kstep;
;             if (last && has_next) S.a_ready(nxt);
;             if constexpr (SP2) {
;             PG8_LDB(B0, 0, 0); PG8_LDB(B1, 0, 1); PG8_SCHED; PG8_LDA(At, 0, 0); PG8_STAGE(PG8_SA(1, 1), a1 + hstep, voffA);
;     ...
;         for (int a = 0; a < 2; ++a)
; #pragma unroll
;             for (int b = 0; b < 2; ++b)
; #pragma unroll
;                 for (int m = 0; m < 4; ++m)
; #pragma unroll
;                     for (int n = 0; n < 2; ++n) acc[a][b][m][n] = (f32x4){0.f, 0.f, 0.f, 0.f};
.LBB0_24:
	s_ashr_i32 s55, s54, 31
	s_lshl_b64 s[76:77], s[54:55], 20
	s_add_u32 s76, s8, s76
	s_addc_u32 s77, s9, s77
	s_and_b64 s[78:79], s[74:75], exec
	s_cselect_b32 s55, s77, s53
	s_cselect_b32 s83, s76, s52
	s_ashr_i32 s73, s72, 31
	s_lshl_b64 s[78:79], s[72:73], 20
	s_add_u32 s78, s0, s78
	s_addc_u32 s79, s1, s79
	s_and_b64 s[80:81], s[74:75], exec
	s_cselect_b32 s73, s79, s5
	s_cselect_b32 s84, s78, s4
	s_add_u32 s80, s52, 0x80080
	s_addc_u32 s81, s53, 0
	s_add_u32 s85, s4, 0x100
	v_mov_b32_e32 v0, 0
	s_addc_u32 s86, s5, 0
	s_mov_b32 s87, -2
	s_cmp_gt_i32 s63, 1
	s_cselect_b32 s98, -2, 0x7fffffff
	v_mov_b32_e32 v1, v0
	v_mov_b32_e32 v2, v0
	v_mov_b32_e32 v3, v0
	v_mov_b32_e32 v4, v0
	v_mov_b32_e32 v5, v0
	v_mov_b32_e32 v6, v0
	v_mov_b32_e32 v7, v0
	v_mov_b32_e32 v8, v0
	v_mov_b32_e32 v9, v0
	v_mov_b32_e32 v10, v0
	v_mov_b32_e32 v11, v0
	v_mov_b32_e32 v12, v0
	v_mov_b32_e32 v13, v0
	v_mov_b32_e32 v14, v0
	v_mov_b32_e32 v15, v0
	v_mov_b32_e32 v24, v0
	v_mov_b32_e32 v25, v0
	v_mov_b32_e32 v26, v0
	v_mov_b32_e32 v27, v0
	v_mov_b32_e32 v28, v0
	v_mov_b32_e32 v29, v0
	v_mov_b32_e32 v30, v0
	v_mov_b32_e32 v31, v0
	v_mov_b32_e32 v40, v0
	v_mov_b32_e32 v41, v0
	v_mov_b32_e32 v42, v0
	v_mov_b32_e32 v43, v0
	v_mov_b32_e32 v44, v0
	v_mov_b32_e32 v45, v0
	v_mov_b32_e32 v46, v0
	v_mov_b32_e32 v47, v0
	v_mov_b32_e32 v16, v0
	v_mov_b32_e32 v17, v0
	v_mov_b32_e32 v18, v0
	v_mov_b32_e32 v19, v0
	v_mov_b32_e32 v20, v0
	v_mov_b32_e32 v21, v0
	v_mov_b32_e32 v22, v0
	v_mov_b32_e32 v23, v0
	v_mov_b32_e32 v32, v0
	v_mov_b32_e32 v33, v0
	v_mov_b32_e32 v34, v0
	v_mov_b32_e32 v35, v0
	v_mov_b32_e32 v36, v0
	v_mov_b32_e32 v37, v0
	v_mov_b32_e32 v38, v0
	v_mov_b32_e32 v39, v0
	v_mov_b32_e32 v48, v0
	v_mov_b32_e32 v49, v0
	v_mov_b32_e32 v50, v0
	v_mov_b32_e32 v51, v0
	v_mov_b32_e32 v52, v0
	v_mov_b32_e32 v53, v0
	v_mov_b32_e32 v54, v0
	v_mov_b32_e32 v55, v0
	v_mov_b32_e32 v56, v0
	v_mov_b32_e32 v57, v0
	v_mov_b32_e32 v58, v0
	v_mov_b32_e32 v59, v0
	v_mov_b32_e32 v60, v0
	v_mov_b32_e32 v61, v0
	v_mov_b32_e32 v62, v0
	v_mov_b32_e32 v63, v0
	v_mov_b32_e32 v64, v0
	v_mov_b32_e32 v65, v0
	v_mov_b32_e32 v66, v0
	v_mov_b32_e32 v67, v0
	v_mov_b32_e32 v68, v0
	v_mov_b32_e32 v69, v0
	v_mov_b32_e32 v70, v0
	v_mov_b32_e32 v71, v0
	v_mov_b32_e32 v72, v0
	v_mov_b32_e32 v73, v0
	v_mov_b32_e32 v74, v0
	v_mov_b32_e32 v75, v0
	v_mov_b32_e32 v76, v0
	v_mov_b32_e32 v77, v0
	v_mov_b32_e32 v78, v0
	v_mov_b32_e32 v79, v0
	v_mov_b32_e32 v88, v0
	v_mov_b32_e32 v89, v0
	v_mov_b32_e32 v90, v0
	v_mov_b32_e32 v91, v0
	v_mov_b32_e32 v92, v0
	v_mov_b32_e32 v93, v0
	v_mov_b32_e32 v94, v0
	v_mov_b32_e32 v95, v0
	v_mov_b32_e32 v104, v0
	v_mov_b32_e32 v105, v0
	v_mov_b32_e32 v106, v0
	v_mov_b32_e32 v107, v0
	v_mov_b32_e32 v108, v0
	v_mov_b32_e32 v109, v0
	v_mov_b32_e32 v110, v0
	v_mov_b32_e32 v111, v0
	v_mov_b32_e32 v80, v0
	v_mov_b32_e32 v81, v0
	v_mov_b32_e32 v82, v0
	v_mov_b32_e32 v83, v0
	v_mov_b32_e32 v84, v0
	v_mov_b32_e32 v85, v0
	v_mov_b32_e32 v86, v0
	v_mov_b32_e32 v87, v0
	v_mov_b32_e32 v96, v0
	v_mov_b32_e32 v97, v0
	v_mov_b32_e32 v98, v0
	v_mov_b32_e32 v99, v0
	v_mov_b32_e32 v100, v0
	v_mov_b32_e32 v101, v0
	v_mov_b32_e32 v102, v0
	v_mov_b32_e32 v103, v0
	v_mov_b32_e32 v112, v0
	v_mov_b32_e32 v113, v0
	v_mov_b32_e32 v114, v0
	v_mov_b32_e32 v115, v0
	v_mov_b32_e32 v116, v0
	v_mov_b32_e32 v117, v0
	v_mov_b32_e32 v118, v0
	v_mov_b32_e32 v119, v0
	v_mov_b32_e32 v120, v0
	v_mov_b32_e32 v121, v0
	v_mov_b32_e32 v122, v0
	v_mov_b32_e32 v123, v0
	v_mov_b32_e32 v124, v0
	v_mov_b32_e32 v125, v0
	v_mov_b32_e32 v126, v0
	v_mov_b32_e32 v127, v0
.LBB0_25:
	s_add_u32 s4, s80, 0xfff80080
	s_addc_u32 s5, s81, -1
	s_add_i32 s88, 0, 0x10000
	s_cmp_eq_u32 s87, 28
	s_cselect_b32 s53, s55, s5
	s_cselect_b32 s52, s83, s4
	s_cselect_b32 s5, s73, s86
	s_cselect_b32 s4, s84, s85
	s_add_i32 s90, 0, 0x14000
	v_add_u32_e32 v154, s88, v139
	v_add_u32_e32 v158, s90, v139
	ds_read_b128 v[142:145], v154
	ds_read_b128 v[146:149], v154 offset:1024
	ds_read_b128 v[150:153], v154 offset:2048
	ds_read_b128 v[154:157], v154 offset:3072
	ds_read_b128 v[164:167], v158
	ds_read_b128 v[168:171], v158 offset:1024
	ds_read_b128 v[172:175], v158 offset:2048
	ds_read_b128 v[176:179], v158 offset:3072
	v_lshl_add_u64 v[158:159], s[80:81], 0, v[134:135]
	s_add_i32 m0, s29, 0xc000
	ds_read_b128 v[180:183], v141
	ds_read_b128 v[184:187], v141 offset:1024
	ds_read_b128 v[188:191], v141 offset:2048
	ds_read_b128 v[192:195], v141 offset:3072
	ds_read_b128 v[196:199], v141 offset:4096
	ds_read_b128 v[222:225], v141 offset:5120
	ds_read_b128 v[226:229], v141 offset:6144
	ds_read_b128 v[230:233], v141 offset:7168
	global_load_lds_dwordx4 v[158:159], off
	v_lshl_add_u64 v[158:159], s[80:81], 0, v[136:137]
	s_add_i32 m0, s29, 0xe000
	s_nop 0
	global_load_lds_dwordx4 v[158:159], off
	s_waitcnt vmcnt(24)
	s_cmp_eq_u32 s87, s98
	s_cbranch_scc1 .Lrx_out_0
	s_waitcnt vmcnt(8)
; #define PG8_STAGE(bufoff, gbase, voff) do { _Pragma("unroll") for (int _i = 0; _i < 2; ++_i) \
;         __builtin_amdgcn_global_load_lds((const unsigned*)((const char*)(gbase) + (voff)[_i]), (PG8_LAS unsigned*)(lds + (bufoff) + ldsw + _i * 8192), 16, 0, 0); } while (0)
; #define PG8_LDA(dst, b, h) do { _Pragma("unroll") for (int m = 0; m < 4; ++m) _Pragma("unroll") for (int k = 0; k < 2; ++k) dst[m][k] = *(const PG8_LAS bf16x8*)(lds + PG8_SA(b, h) + aoff + m * 2048 + k * 1024); } while (0)
; #define PG8_MMA(ai, bj, At, Bt) do { __builtin_amdgcn_s_setprio(1); _Pragma("unroll") for (int m = 0; m < 4; ++m) _Pragma("unroll") for (int n = 0; n < 2; ++n) _Pragma("unroll") for (int k = 0; k < 2; ++k) \
;         acc[ai][bj][m][n] = __builtin_amdgcn_mfma_f32_16x16x32_bf16(Bt[n][k], At[m][k], acc[ai][bj][m][n], 0, 0, 0); __builtin_amdgcn_s_setprio(0); } while (0)
; #define PG8_WAIT_V(n) asm volatile("s_waitcnt vmcnt(" #n ")" ::: "memory")
; #define PG8_WAIT_L(n) asm volatile("s_waitcnt lgkmcnt(" #n ")" ::: "memory")
; #define PG8_BAR __builtin_amdgcn_s_barrier()
; #define PG8_SCHED __builtin_amdgcn_sched_barrier(0)
; template <class Epi, class Sched, bool ALIGN_EPI = false, bool SP2 = false>
; __device__ __forceinline__ void gemm_phase(PG8_LAS unsigned char* lds, const Gemm g, const Sched& S, const Epi& E) {
;     ...
;             PG8_WAIT_V(8); PG8_WAIT_L(0); PG8_BAR; PG8_MMA(0, 0, At, B0); PG8_MMA(0, 1, At, B1); PG8_BAR; PG8_SCHED;
;             PG8_LDA(At, 0, 1); PG8_STAGE(PG8_SB(0, 0), b2, voffB); PG8_STAGE(PG8_SB(0, 1), b2 + hstep, voffB); PG8_STAGE(PG8_SA(0, 0), a2, voffA);
;             PG8_WAIT_V(8); PG8_WAIT_L(0); PG8_BAR; PG8_MMA(1, 0, At, B0); PG8_MMA(1, 1, At, B1); PG8_BAR; PG8_SCHED;
.Lrx_out_0:
	s_waitcnt lgkmcnt(0)
	s_barrier
	s_setprio 1
	s_waitcnt lgkmcnt(0)
	v_mfma_f32_16x16x32_bf16 v[124:127], v[142:145], v[180:183], v[124:127]
	v_mfma_f32_16x16x32_bf16 v[120:123], v[150:153], v[180:183], v[120:123]
	v_mfma_f32_16x16x32_bf16 v[116:119], v[142:145], v[188:191], v[116:119]
	v_mfma_f32_16x16x32_bf16 v[112:115], v[150:153], v[188:191], v[112:115]
	v_mfma_f32_16x16x32_bf16 v[100:103], v[142:145], v[196:199], v[100:103]
	v_mfma_f32_16x16x32_bf16 v[96:99], v[150:153], v[196:199], v[96:99]
	v_mfma_f32_16x16x32_bf16 v[84:87], v[142:145], v[226:229], v[84:87]
	v_mfma_f32_16x16x32_bf16 v[80:83], v[150:153], v[226:229], v[80:83]
	v_mfma_f32_16x16x32_bf16 v[124:127], v[146:149], v[184:187], v[124:127]
	v_mfma_f32_16x16x32_bf16 v[120:123], v[154:157], v[184:187], v[120:123]
	v_mfma_f32_16x16x32_bf16 v[116:119], v[146:149], v[192:195], v[116:119]
	v_mfma_f32_16x16x32_bf16 v[112:115], v[154:157], v[192:195], v[112:115]
	v_mfma_f32_16x16x32_bf16 v[100:103], v[146:149], v[222:225], v[100:103]
	v_mfma_f32_16x16x32_bf16 v[96:99], v[154:157], v[222:225], v[96:99]
	v_mfma_f32_16x16x32_bf16 v[84:87], v[146:149], v[230:233], v[84:87]
	v_mfma_f32_16x16x32_bf16 v[80:83], v[154:157], v[230:233], v[80:83]
	s_setprio 0
	s_setprio 1
	v_mfma_f32_16x16x32_bf16 v[108:111], v[164:167], v[180:183], v[108:111]
	v_mfma_f32_16x16x32_bf16 v[104:107], v[172:175], v[180:183], v[104:107]
	v_mfma_f32_16x16x32_bf16 v[92:95], v[164:167], v[188:191], v[92:95]
	v_mfma_f32_16x16x32_bf16 v[88:91], v[172:175], v[188:191], v[88:91]
	v_mfma_f32_16x16x32_bf16 v[76:79], v[164:167], v[196:199], v[76:79]
	v_mfma_f32_16x16x32_bf16 v[72:75], v[172:175], v[196:199], v[72:75]
	v_mfma_f32_16x16x32_bf16 v[68:71], v[164:167], v[226:229], v[68:71]
	v_mfma_f32_16x16x32_bf16 v[64:67], v[172:175], v[226:229], v[64:67]
	v_mfma_f32_16x16x32_bf16 v[108:111], v[168:171], v[184:187], v[108:111]
	v_mfma_f32_16x16x32_bf16 v[104:107], v[176:179], v[184:187], v[104:107]
	v_mfma_f32_16x16x32_bf16 v[92:95], v[168:171], v[192:195], v[92:95]
	v_mfma_f32_16x16x32_bf16 v[88:91], v[176:179], v[192:195], v[88:91]
	v_mfma_f32_16x16x32_bf16 v[76:79], v[168:171], v[222:225], v[76:79]
	v_mfma_f32_16x16x32_bf16 v[72:75], v[176:179], v[222:225], v[72:75]
	v_mfma_f32_16x16x32_bf16 v[68:71], v[168:171], v[230:233], v[68:71]
	v_mfma_f32_16x16x32_bf16 v[64:67], v[176:179], v[230:233], v[64:67]
	s_setprio 0
	s_barrier
	s_add_i32 s88, s88, s28
	v_lshl_add_u64 v[158:159], s[4:5], 0, v[160:161]
	s_mov_b32 m0, s88
	ds_read_b128 v[180:183], v141 offset:16384
	ds_read_b128 v[184:187], v141 offset:17408
	ds_read_b128 v[188:191], v141 offset:18432
	ds_read_b128 v[192:195], v141 offset:19456
	ds_read_b128 v[196:199], v141 offset:20480
	ds_read_b128 v[222:225], v141 offset:21504
	ds_read_b128 v[226:229], v141 offset:22528
	ds_read_b128 v[230:233], v141 offset:23552
	global_load_lds_dwordx4 v[158:159], off
	s_add_i32 m0, s88, 0x2000
	s_add_u32 s88, s4, 0x80000
	v_lshl_add_u64 v[200:201], s[4:5], 0, v[128:129]
	s_addc_u32 s89, s5, 0
	s_add_i32 s90, s90, s28
	global_load_lds_dwordx4 v[200:201], off
	v_lshl_add_u64 v[234:235], s[88:89], 0, v[160:161]
	s_mov_b32 m0, s90
	v_lshl_add_u64 v[236:237], s[52:53], 0, v[130:131]
	global_load_lds_dwordx4 v[234:235], off
	v_lshl_add_u64 v[234:235], s[88:89], 0, v[128:129]
	s_add_i32 m0, s90, 0x2000
	s_nop 0
	global_load_lds_dwordx4 v[234:235], off
	v_lshl_add_u64 v[234:235], s[52:53], 0, v[132:133]
	s_mov_b32 m0, s29
	s_nop 0
	global_load_lds_dwordx4 v[234:235], off
	s_mov_b32 m0, s45
	s_nop 0
	global_load_lds_dwordx4 v[236:237], off
	s_waitcnt vmcnt(24)
	s_cmp_eq_u32 s87, s98
	s_cbranch_scc1 .Lrx_out_1
	s_waitcnt vmcnt(8)
.Lrx_out_1:
	s_waitcnt lgkmcnt(0)
	s_barrier
	s_setprio 1
	s_waitcnt lgkmcnt(0)
	v_mfma_f32_16x16x32_bf16 v[60:63], v[142:145], v[180:183], v[60:63]
	v_mfma_f32_16x16x32_bf16 v[56:59], v[150:153], v[180:183], v[56:59]
	v_mfma_f32_16x16x32_bf16 v[52:55], v[142:145], v[188:191], v[52:55]
	v_mfma_f32_16x16x32_bf16 v[48:51], v[150:153], v[188:191], v[48:51]
	v_mfma_f32_16x16x32_bf16 v[36:39], v[142:145], v[196:199], v[36:39]
	v_mfma_f32_16x16x32_bf16 v[32:35], v[150:153], v[196:199], v[32:35]
	v_mfma_f32_16x16x32_bf16 v[20:23], v[142:145], v[226:229], v[20:23]
	v_mfma_f32_16x16x32_bf16 v[16:19], v[150:153], v[226:229], v[16:19]
	v_mfma_f32_16x16x32_bf16 v[60:63], v[146:149], v[184:187], v[60:63]
	v_mfma_f32_16x16x32_bf16 v[56:59], v[154:157], v[184:187], v[56:59]
	v_mfma_f32_16x16x32_bf16 v[52:55], v[146:149], v[192:195], v[52:55]
	v_mfma_f32_16x16x32_bf16 v[48:51], v[154:157], v[192:195], v[48:51]
	v_mfma_f32_16x16x32_bf16 v[36:39], v[146:149], v[222:225], v[36:39]
	v_mfma_f32_16x16x32_bf16 v[32:35], v[154:157], v[222:225], v[32:35]
	v_mfma_f32_16x16x32_bf16 v[20:23], v[146:149], v[230:233], v[20:23]
	v_mfma_f32_16x16x32_bf16 v[16:19], v[154:157], v[230:233], v[16:19]
	s_setprio 0
	s_setprio 1
	v_mfma_f32_16x16x32_bf16 v[44:47], v[164:167], v[180:183], v[44:47]
	v_mfma_f32_16x16x32_bf16 v[40:43], v[172:175], v[180:183], v[40:43]
	v_mfma_f32_16x16x32_bf16 v[28:31], v[164:167], v[188:191], v[28:31]
	v_mfma_f32_16x16x32_bf16 v[24:27], v[172:175], v[188:191], v[24:27]
	v_mfma_f32_16x16x32_bf16 v[12:15], v[164:167], v[196:199], v[12:15]
	v_mfma_f32_16x16x32_bf16 v[8:11], v[172:175], v[196:199], v[8:11]
	v_mfma_f32_16x16x32_bf16 v[4:7], v[164:167], v[226:229], v[4:7]
	v_mfma_f32_16x16x32_bf16 v[0:3], v[172:175], v[226:229], v[0:3]
	v_mfma_f32_16x16x32_bf16 v[44:47], v[168:171], v[184:187], v[44:47]
	v_mfma_f32_16x16x32_bf16 v[40:43], v[176:179], v[184:187], v[40:43]
	v_mfma_f32_16x16x32_bf16 v[28:31], v[168:171], v[192:195], v[28:31]
	v_mfma_f32_16x16x32_bf16 v[24:27], v[176:179], v[192:195], v[24:27]
	v_mfma_f32_16x16x32_bf16 v[12:15], v[168:171], v[222:225], v[12:15]
	v_mfma_f32_16x16x32_bf16 v[8:11], v[176:179], v[222:225], v[8:11]
	v_mfma_f32_16x16x32_bf16 v[4:7], v[168:171], v[230:233], v[4:7]
	v_mfma_f32_16x16x32_bf16 v[0:3], v[176:179], v[230:233], v[0:3]
	s_setprio 0
	s_barrier
; #define PG8_STAGE(bufoff, gbase, voff) do { _Pragma("unroll") for (int _i = 0; _i < 2; ++_i) \
;         __builtin_amdgcn_global_load_lds((const unsigned*)((const char*)(gbase) + (voff)[_i]), (PG8_LAS unsigned*)(lds + (bufoff) + ldsw + _i * 8192), 16, 0, 0); } while (0)
; #define PG8_LDA(dst, b, h) do { _Pragma("unroll") for (int m = 0; m < 4; ++m) _Pragma("unroll") for (int k = 0; k < 2; ++k) dst[m][k] = *(const PG8_LAS bf16x8*)(lds + PG8_SA(b, h) + aoff + m * 2048 + k * 1024); } while (0)
; #define PG8_LDB(dst, b, h) do { _Pragma("unroll") for (int n = 0; n < 2; ++n) _Pragma("unroll") for (int k = 0; k < 2; ++k) dst[n][k] = *(const PG8_LAS bf16x8*)(lds + PG8_SB(b, h) + boff + n * 2048 + k * 1024); } while (0)
; #define PG8_MMA(ai, bj, At, Bt) do { __builtin_amdgcn_s_setprio(1); _Pragma("unroll") for (int m = 0; m < 4; ++m) _Pragma("unroll") for (int n = 0; n < 2; ++n) _Pragma("unroll") for (int k = 0; k < 2; ++k) \
;         acc[ai][bj][m][n] = __builtin_amdgcn_mfma_f32_16x16x32_bf16(Bt[n][k], At[m][k], acc[ai][bj][m][n], 0, 0, 0); __builtin_amdgcn_s_setprio(0); } while (0)
; #define PG8_WAIT_V(n) asm volatile("s_waitcnt vmcnt(" #n ")" ::: "memory")
; #define PG8_WAIT_L(n) asm volatile("s_waitcnt lgkmcnt(" #n ")" ::: "memory")
; #define PG8_BAR __builtin_amdgcn_s_barrier()
; #define PG8_SCHED __builtin_amdgcn_sched_barrier(0)
; template <class Epi, class Sched, bool ALIGN_EPI = false, bool SP2 = false>
; __device__ __forceinline__ void gemm_phase(PG8_LAS unsigned char* lds, const Gemm g, const Sched& S, const Epi& E) {
;     ...
;             PG8_LDB(B0, 1, 0); PG8_LDB(B1, 1, 1); PG8_SCHED; PG8_LDA(At, 1, 0); PG8_STAGE(PG8_SA(0, 1), a2 + hstep, voffA);
;             PG8_WAIT_V(8); PG8_WAIT_L(0); PG8_BAR; PG8_MMA(0, 0, At, B0); PG8_MMA(0, 1, At, B1); PG8_BAR; PG8_SCHED;
	s_add_i32 s88, 0, 0x18000
	s_add_i32 s89, 0, 0x1c000
	v_add_u32_e32 v154, s88, v139
	v_add_u32_e32 v163, s89, v139
	ds_read_b128 v[142:145], v154
	ds_read_b128 v[146:149], v154 offset:1024
	ds_read_b128 v[150:153], v154 offset:2048
	ds_read_b128 v[154:157], v154 offset:3072
	ds_read_b128 v[164:167], v163
	ds_read_b128 v[168:171], v163 offset:1024
	ds_read_b128 v[172:175], v163 offset:2048
	ds_read_b128 v[176:179], v163 offset:3072
	s_add_u32 s52, s52, 0x80000
	s_addc_u32 s53, s53, 0
	s_mov_b32 m0, s56
	v_lshl_add_u64 v[238:239], s[52:53], 0, v[132:133]
	ds_read_b128 v[180:183], v141 offset:32768
	ds_read_b128 v[184:187], v141 offset:33792
	ds_read_b128 v[188:191], v141 offset:34816
	ds_read_b128 v[192:195], v141 offset:35840
	ds_read_b128 v[196:199], v141 offset:36864
	ds_read_b128 v[222:225], v141 offset:37888
	ds_read_b128 v[226:229], v141 offset:38912
	ds_read_b128 v[230:233], v141 offset:39936
	global_load_lds_dwordx4 v[238:239], off
	v_lshl_add_u64 v[238:239], s[52:53], 0, v[130:131]
	s_mov_b32 m0, s57
	s_nop 0
	global_load_lds_dwordx4 v[238:239], off
	s_waitcnt vmcnt(8)
	s_waitcnt lgkmcnt(0)
	s_barrier
	s_setprio 1
	s_waitcnt lgkmcnt(0)
	v_mfma_f32_16x16x32_bf16 v[124:127], v[142:145], v[180:183], v[124:127]
	v_mfma_f32_16x16x32_bf16 v[120:123], v[150:153], v[180:183], v[120:123]
	v_mfma_f32_16x16x32_bf16 v[116:119], v[142:145], v[188:191], v[116:119]
	v_mfma_f32_16x16x32_bf16 v[112:115], v[150:153], v[188:191], v[112:115]
	v_mfma_f32_16x16x32_bf16 v[100:103], v[142:145], v[196:199], v[100:103]
	v_mfma_f32_16x16x32_bf16 v[96:99], v[150:153], v[196:199], v[96:99]
	v_mfma_f32_16x16x32_bf16 v[84:87], v[142:145], v[226:229], v[84:87]
	v_mfma_f32_16x16x32_bf16 v[80:83], v[150:153], v[226:229], v[80:83]
	v_mfma_f32_16x16x32_bf16 v[124:127], v[146:149], v[184:187], v[124:127]
	v_mfma_f32_16x16x32_bf16 v[120:123], v[154:157], v[184:187], v[120:123]
	v_mfma_f32_16x16x32_bf16 v[116:119], v[146:149], v[192:195], v[116:119]
	v_mfma_f32_16x16x32_bf16 v[112:115], v[154:157], v[192:195], v[112:115]
	v_mfma_f32_16x16x32_bf16 v[100:103], v[146:149], v[222:225], v[100:103]
	v_mfma_f32_16x16x32_bf16 v[96:99], v[154:157], v[222:225], v[96:99]
	v_mfma_f32_16x16x32_bf16 v[84:87], v[146:149], v[230:233], v[84:87]
	v_mfma_f32_16x16x32_bf16 v[80:83], v[154:157], v[230:233], v[80:83]
	s_setprio 0
	s_setprio 1
	v_mfma_f32_16x16x32_bf16 v[108:111], v[164:167], v[180:183], v[108:111]
	v_mfma_f32_16x16x32_bf16 v[104:107], v[172:175], v[180:183], v[104:107]
	v_mfma_f32_16x16x32_bf16 v[92:95], v[164:167], v[188:191], v[92:95]
	v_mfma_f32_16x16x32_bf16 v[88:91], v[172:175], v[188:191], v[88:91]
	v_mfma_f32_16x16x32_bf16 v[76:79], v[164:167], v[196:199], v[76:79]
	v_mfma_f32_16x16x32_bf16 v[72:75], v[172:175], v[196:199], v[72:75]
	v_mfma_f32_16x16x32_bf16 v[68:71], v[164:167], v[226:229], v[68:71]
	v_mfma_f32_16x16x32_bf16 v[64:67], v[172:175], v[226:229], v[64:67]
	v_mfma_f32_16x16x32_bf16 v[108:111], v[168:171], v[184:187], v[108:111]
	v_mfma_f32_16x16x32_bf16 v[104:107], v[176:179], v[184:187], v[104:107]
	v_mfma_f32_16x16x32_bf16 v[92:95], v[168:171], v[192:195], v[92:95]
	v_mfma_f32_16x16x32_bf16 v[88:91], v[176:179], v[192:195], v[88:91]
	v_mfma_f32_16x16x32_bf16 v[76:79], v[168:171], v[222:225], v[76:79]
	v_mfma_f32_16x16x32_bf16 v[72:75], v[176:179], v[222:225], v[72:75]
	v_mfma_f32_16x16x32_bf16 v[68:71], v[168:171], v[230:233], v[68:71]
	v_mfma_f32_16x16x32_bf16 v[64:67], v[176:179], v[230:233], v[64:67]
	s_setprio 0
	s_barrier
; #define PG8_STAGE(bufoff, gbase, voff) do { _Pragma("unroll") for (int _i = 0; _i < 2; ++_i) \
;         __builtin_amdgcn_global_load_lds((const unsigned*)((const char*)(gbase) + (voff)[_i]), (PG8_LAS unsigned*)(lds + (bufoff) + ldsw + _i * 8192), 16, 0, 0); } while (0)
; #define PG8_LDA(dst, b, h) do { _Pragma("unroll") for (int m = 0; m < 4; ++m) _Pragma("unroll") for (int k = 0; k < 2; ++k) dst[m][k] = *(const PG8_LAS bf16x8*)(lds + PG8_SA(b, h) + aoff + m * 2048 + k * 1024); } while (0)
; #define PG8_MMA(ai, bj, At, Bt) do { __builtin_amdgcn_s_setprio(1); _Pragma("unroll") for (int m = 0; m < 4; ++m) _Pragma("unroll") for (int n = 0; n < 2; ++n) _Pragma("unroll") for (int k = 0; k < 2; ++k) \
;         acc[ai][bj][m][n] = __builtin_amdgcn_mfma_f32_16x16x32_bf16(Bt[n][k], At[m][k], acc[ai][bj][m][n], 0, 0, 0); __builtin_amdgcn_s_setprio(0); } while (0)
; #define PG8_WAIT_V(n) asm volatile("s_waitcnt vmcnt(" #n ")" ::: "memory")
; #define PG8_WAIT_L(n) asm volatile("s_waitcnt lgkmcnt(" #n ")" ::: "memory")
; #define PG8_BAR __builtin_amdgcn_s_barrier()
; #define PG8_SCHED __builtin_amdgcn_sched_barrier(0)
; template <class Epi, class Sched, bool ALIGN_EPI = false, bool SP2 = false>
; __device__ __forceinline__ void gemm_phase(PG8_LAS unsigned char* lds, const Gemm g, const Sched& S, const Epi& E) {
;     ...
;             PG8_LDA(At, 1, 1); PG8_STAGE(PG8_SB(1, 0), b3, voffB); PG8_STAGE(PG8_SB(1, 1), b3 + hstep, voffB); PG8_STAGE(PG8_SA(1, 0), a3, voffA);
;             PG8_WAIT_V(8); PG8_WAIT_L(0); PG8_BAR; PG8_MMA(1, 0, At, B0); PG8_MMA(1, 1, At, B1); PG8_BAR; PG8_SCHED;
	s_add_i32 s52, s88, s28
	v_lshl_add_u64 v[158:159], v[158:159], 0, s[30:31]
	s_mov_b32 m0, s52
	ds_read_b128 v[180:183], v141 offset:49152
	ds_read_b128 v[184:187], v141 offset:50176
	ds_read_b128 v[188:191], v141 offset:51200
	ds_read_b128 v[192:195], v141 offset:52224
	ds_read_b128 v[196:199], v141 offset:53248
	ds_read_b128 v[222:225], v141 offset:54272
	ds_read_b128 v[226:229], v141 offset:55296
	ds_read_b128 v[230:233], v141 offset:56320
	global_load_lds_dwordx4 v[158:159], off
	s_add_i32 m0, s52, 0x2000
	s_add_u32 s4, s4, 0x80080
	v_lshl_add_u64 v[158:159], v[200:201], 0, s[30:31]
	s_addc_u32 s5, s5, 0
	s_add_i32 s52, s89, s28
	global_load_lds_dwordx4 v[158:159], off
	v_lshl_add_u64 v[158:159], s[4:5], 0, v[160:161]
	s_mov_b32 m0, s52
	s_nop 0
	global_load_lds_dwordx4 v[158:159], off
	v_lshl_add_u64 v[158:159], s[4:5], 0, v[128:129]
	s_add_i32 m0, s52, 0x2000
	s_nop 0
	global_load_lds_dwordx4 v[158:159], off
	v_lshl_add_u64 v[158:159], v[234:235], 0, s[30:31]
	s_mov_b32 m0, s24
	s_nop 0
	global_load_lds_dwordx4 v[158:159], off
	v_lshl_add_u64 v[158:159], v[236:237], 0, s[30:31]
	s_mov_b32 m0, s59
	s_nop 0
	global_load_lds_dwordx4 v[158:159], off
	s_waitcnt vmcnt(8)
	s_waitcnt lgkmcnt(0)
	s_barrier
	s_setprio 1
	s_waitcnt lgkmcnt(0)
	v_mfma_f32_16x16x32_bf16 v[60:63], v[142:145], v[180:183], v[60:63]
	v_mfma_f32_16x16x32_bf16 v[56:59], v[150:153], v[180:183], v[56:59]
	v_mfma_f32_16x16x32_bf16 v[52:55], v[142:145], v[188:191], v[52:55]
	v_mfma_f32_16x16x32_bf16 v[48:51], v[150:153], v[188:191], v[48:51]
	v_mfma_f32_16x16x32_bf16 v[36:39], v[142:145], v[196:199], v[36:39]
	v_mfma_f32_16x16x32_bf16 v[32:35], v[150:153], v[196:199], v[32:35]
	v_mfma_f32_16x16x32_bf16 v[20:23], v[142:145], v[226:229], v[20:23]
	v_mfma_f32_16x16x32_bf16 v[16:19], v[150:153], v[226:229], v[16:19]
	v_mfma_f32_16x16x32_bf16 v[60:63], v[146:149], v[184:187], v[60:63]
	v_mfma_f32_16x16x32_bf16 v[56:59], v[154:157], v[184:187], v[56:59]
	v_mfma_f32_16x16x32_bf16 v[52:55], v[146:149], v[192:195], v[52:55]
	v_mfma_f32_16x16x32_bf16 v[48:51], v[154:157], v[192:195], v[48:51]
	v_mfma_f32_16x16x32_bf16 v[36:39], v[146:149], v[222:225], v[36:39]
	v_mfma_f32_16x16x32_bf16 v[32:35], v[154:157], v[222:225], v[32:35]
	v_mfma_f32_16x16x32_bf16 v[20:23], v[146:149], v[230:233], v[20:23]
	v_mfma_f32_16x16x32_bf16 v[16:19], v[154:157], v[230:233], v[16:19]
	s_setprio 0
	s_setprio 1
	v_mfma_f32_16x16x32_bf16 v[44:47], v[164:167], v[180:183], v[44:47]
	v_mfma_f32_16x16x32_bf16 v[40:43], v[172:175], v[180:183], v[40:43]
	v_mfma_f32_16x16x32_bf16 v[28:31], v[164:167], v[188:191], v[28:31]
	v_mfma_f32_16x16x32_bf16 v[24:27], v[172:175], v[188:191], v[24:27]
	v_mfma_f32_16x16x32_bf16 v[12:15], v[164:167], v[196:199], v[12:15]
	v_mfma_f32_16x16x32_bf16 v[8:11], v[172:175], v[196:199], v[8:11]
	v_mfma_f32_16x16x32_bf16 v[4:7], v[164:167], v[226:229], v[4:7]
	v_mfma_f32_16x16x32_bf16 v[0:3], v[172:175], v[226:229], v[0:3]
	v_mfma_f32_16x16x32_bf16 v[44:47], v[168:171], v[184:187], v[44:47]
	v_mfma_f32_16x16x32_bf16 v[40:43], v[176:179], v[184:187], v[40:43]
	v_mfma_f32_16x16x32_bf16 v[28:31], v[168:171], v[192:195], v[28:31]
	v_mfma_f32_16x16x32_bf16 v[24:27], v[176:179], v[192:195], v[24:27]
	v_mfma_f32_16x16x32_bf16 v[12:15], v[168:171], v[222:225], v[12:15]
	v_mfma_f32_16x16x32_bf16 v[8:11], v[176:179], v[222:225], v[8:11]
	v_mfma_f32_16x16x32_bf16 v[4:7], v[168:171], v[230:233], v[4:7]
	v_mfma_f32_16x16x32_bf16 v[0:3], v[176:179], v[230:233], v[0:3]
	s_setprio 0
	s_barrier
	s_add_i32 s87, s87, 2
	s_add_u32 s80, s80, 0x100
	s_addc_u32 s81, s81, 0
	s_add_u32 s85, s85, 0x100
	s_addc_u32 s86, s86, 0
	s_cmp_gt_u32 s87, 29
	s_cbranch_scc0 .LBB0_25
	s_and_b64 vcc, exec, s[42:43]
	s_cbranch_vccz .LBB0_28
	s_barrier

;     __host__ __device__ bool next(int i, Unit& u) const { if (!base.next(i >> 1, u)) return false; if (i & 1) { u.pm += 64; u.pn += 8; } return true; }
; #define PG8_STAGE(bufoff, gbase, voff) do { _Pragma("unroll") for (int _i = 0; _i < 2; ++_i) \
;         __builtin_amdgcn_global_load_lds((const unsigned*)((const char*)(gbase) + (voff)[_i]), (PG8_LAS unsigned*)(lds + (bufoff) + ldsw + _i * 8192), 16, 0, 0); } while (0)
; #define PG8_LDA(dst, b, h) do { _Pragma("unroll") for (int m = 0; m < 4; ++m) _Pragma("unroll") for (int k = 0; k < 2; ++k) dst[m][k] = *(const PG8_LAS bf16x8*)(lds + PG8_SA(b, h) + aoff + m * 2048 + k * 1024); } while (0)
; #define PG8_LDB(dst, b, h) do { _Pragma("unroll") for (int n = 0; n < 2; ++n) _Pragma("unroll") for (int k = 0; k < 2; ++k) dst[n][k] = *(const PG8_LAS bf16x8*)(lds + PG8_SB(b, h) + boff + n * 2048 + k * 1024); } while (0)
; #define PG8_SCHED __builtin_amdgcn_sched_barrier(0)
; template <class Epi, class Sched, bool ALIGN_EPI = false, bool SP2 = false>
; __device__ __forceinline__ void gemm_phase(PG8_LAS unsigned char* lds, const Gemm g, const Sched& S, const Epi& E) {
;     ...
;         const bool has_next = S.next(ui + 1, nxt);
;         const char* nA = has_next ? (const char*)g.A + (size_t)nxt.pm * tstep : cA; const char* nB = has_next ? (const char*)g.Bt + (size_t)nxt.pn * tstep : cB;
;         for (int t = 0; t < nt; t += 2) {
;             const bool last = (t == nt - 2);
;             const char* a1 = cA + (size_t)(t + 1) * kstep;
;             const char* a2 = last ? nA : cA + (size_t)(t + 2) * kstep; const char* b2 = last ? nB : cB + (size_t)(t + 2) * kstep;
;             const char* a3 = a2 + kstep; const char* b3 = b2 + kstep;
;             if (last && has_next) S.a_ready(nxt);
;             if constexpr (SP2) {
;             PG8_LDB(B0, 0, 0); PG8_LDB(B1, 0, 1); PG8_SCHED; PG8_LDA(At, 0, 0); PG8_STAGE(PG8_SA(1, 1), a1 + hstep, voffA);
;     ...
;         for (int a = 0; a < 2; ++a)
; #pragma unroll
;             for (int b = 0; b < 2; ++b)
; #pragma unroll
;                 for (int m = 0; m < 4; ++m)
; #pragma unroll
;                     for (int n = 0; n < 2; ++n) acc[a][b][m][n] = (f32x4){0.f, 0.f, 0.f, 0.f};
.LBB0_51:
	s_add_u32 s81, s4, 0x100
	v_mov_b32_e32 v0, 0
	s_addc_u32 s82, s5, 0
	s_mov_b32 s83, -2
	s_cmp_gt_i32 s77, 1
	s_cselect_b32 s98, -2, 0x7fffffff
	v_mov_b32_e32 v1, v0
	v_mov_b32_e32 v2, v0
	v_mov_b32_e32 v3, v0
	v_mov_b32_e32 v4, v0
	v_mov_b32_e32 v5, v0
	v_mov_b32_e32 v6, v0
	v_mov_b32_e32 v7, v0
	v_mov_b32_e32 v8, v0
	v_mov_b32_e32 v9, v0
	v_mov_b32_e32 v10, v0
	v_mov_b32_e32 v11, v0
	v_mov_b32_e32 v12, v0
	v_mov_b32_e32 v13, v0
	v_mov_b32_e32 v14, v0
	v_mov_b32_e32 v15, v0
	v_mov_b32_e32 v24, v0
	v_mov_b32_e32 v25, v0
	v_mov_b32_e32 v26, v0
	v_mov_b32_e32 v27, v0
	v_mov_b32_e32 v28, v0
	v_mov_b32_e32 v29, v0
	v_mov_b32_e32 v30, v0
	v_mov_b32_e32 v31, v0
	v_mov_b32_e32 v40, v0
	v_mov_b32_e32 v41, v0
	v_mov_b32_e32 v42, v0
	v_mov_b32_e32 v43, v0
	v_mov_b32_e32 v44, v0
	v_mov_b32_e32 v45, v0
	v_mov_b32_e32 v46, v0
	v_mov_b32_e32 v47, v0
	v_mov_b32_e32 v16, v0
	v_mov_b32_e32 v17, v0
	v_mov_b32_e32 v18, v0
	v_mov_b32_e32 v19, v0
	v_mov_b32_e32 v20, v0
	v_mov_b32_e32 v21, v0
	v_mov_b32_e32 v22, v0
	v_mov_b32_e32 v23, v0
	v_mov_b32_e32 v32, v0
	v_mov_b32_e32 v33, v0
	v_mov_b32_e32 v34, v0
	v_mov_b32_e32 v35, v0
	v_mov_b32_e32 v36, v0
	v_mov_b32_e32 v37, v0
	v_mov_b32_e32 v38, v0
	v_mov_b32_e32 v39, v0
	v_mov_b32_e32 v48, v0
	v_mov_b32_e32 v49, v0
	v_mov_b32_e32 v50, v0
	v_mov_b32_e32 v51, v0
	v_mov_b32_e32 v52, v0
	v_mov_b32_e32 v53, v0
	v_mov_b32_e32 v54, v0
	v_mov_b32_e32 v55, v0
	v_mov_b32_e32 v56, v0
	v_mov_b32_e32 v57, v0
	v_mov_b32_e32 v58, v0
	v_mov_b32_e32 v59, v0
	v_mov_b32_e32 v60, v0
	v_mov_b32_e32 v61, v0
	v_mov_b32_e32 v62, v0
	v_mov_b32_e32 v63, v0
	v_mov_b32_e32 v64, v0
	v_mov_b32_e32 v65, v0
	v_mov_b32_e32 v66, v0
	v_mov_b32_e32 v67, v0
	v_mov_b32_e32 v68, v0
	v_mov_b32_e32 v69, v0
	v_mov_b32_e32 v70, v0
	v_mov_b32_e32 v71, v0
	v_mov_b32_e32 v72, v0
	v_mov_b32_e32 v73, v0
	v_mov_b32_e32 v74, v0
	v_mov_b32_e32 v75, v0
	v_mov_b32_e32 v76, v0
	v_mov_b32_e32 v77, v0
	v_mov_b32_e32 v78, v0
	v_mov_b32_e32 v79, v0
	v_mov_b32_e32 v88, v0
	v_mov_b32_e32 v89, v0
	v_mov_b32_e32 v90, v0
	v_mov_b32_e32 v91, v0
	v_mov_b32_e32 v92, v0
	v_mov_b32_e32 v93, v0
	v_mov_b32_e32 v94, v0
	v_mov_b32_e32 v95, v0
	v_mov_b32_e32 v104, v0
	v_mov_b32_e32 v105, v0
	v_mov_b32_e32 v106, v0
	v_mov_b32_e32 v107, v0
	v_mov_b32_e32 v108, v0
	v_mov_b32_e32 v109, v0
	v_mov_b32_e32 v110, v0
	v_mov_b32_e32 v111, v0
	v_mov_b32_e32 v80, v0
	v_mov_b32_e32 v81, v0
	v_mov_b32_e32 v82, v0
	v_mov_b32_e32 v83, v0
	v_mov_b32_e32 v84, v0
	v_mov_b32_e32 v85, v0
	v_mov_b32_e32 v86, v0
	v_mov_b32_e32 v87, v0
	v_mov_b32_e32 v96, v0
	v_mov_b32_e32 v97, v0
	v_mov_b32_e32 v98, v0
	v_mov_b32_e32 v99, v0
	v_mov_b32_e32 v100, v0
	v_mov_b32_e32 v101, v0
	v_mov_b32_e32 v102, v0
	v_mov_b32_e32 v103, v0
	v_mov_b32_e32 v112, v0
	v_mov_b32_e32 v113, v0
	v_mov_b32_e32 v114, v0
	v_mov_b32_e32 v115, v0
	v_mov_b32_e32 v116, v0
	v_mov_b32_e32 v117, v0
	v_mov_b32_e32 v118, v0
	v_mov_b32_e32 v119, v0
	v_mov_b32_e32 v120, v0
	v_mov_b32_e32 v121, v0
	v_mov_b32_e32 v122, v0
	v_mov_b32_e32 v123, v0
	v_mov_b32_e32 v124, v0
	v_mov_b32_e32 v125, v0
	v_mov_b32_e32 v126, v0
	v_mov_b32_e32 v127, v0
.LBB0_52:
	s_add_u32 s4, s72, 0x100
	s_addc_u32 s5, s73, 0
	s_add_i32 s84, 0, 0x10000
	s_cmpk_eq_i32 s83, 0x54
	s_cselect_b32 s57, s45, s5
	s_cselect_b32 s56, s44, s4
	s_cselect_b32 s53, s55, s82
	s_cselect_b32 s52, s54, s81
	s_add_i32 s85, 0, 0x14000
	v_add_u32_e32 v154, s84, v139
	v_add_u32_e32 v158, s85, v139
	ds_read_b128 v[142:145], v154
	ds_read_b128 v[146:149], v154 offset:1024
	ds_read_b128 v[150:153], v154 offset:2048
	ds_read_b128 v[154:157], v154 offset:3072
	ds_read_b128 v[164:167], v158
	ds_read_b128 v[168:171], v158 offset:1024
	ds_read_b128 v[172:175], v158 offset:2048
	ds_read_b128 v[176:179], v158 offset:3072
	v_lshl_add_u64 v[158:159], s[72:73], 0, v[134:135]
	s_add_i32 m0, s28, 0xc000
	ds_read_b128 v[180:183], v141
	ds_read_b128 v[184:187], v141 offset:1024
	ds_read_b128 v[188:191], v141 offset:2048
	ds_read_b128 v[192:195], v141 offset:3072
	ds_read_b128 v[196:199], v141 offset:4096
	ds_read_b128 v[222:225], v141 offset:5120
	ds_read_b128 v[226:229], v141 offset:6144
	ds_read_b128 v[230:233], v141 offset:7168
	global_load_lds_dwordx4 v[158:159], off
	v_lshl_add_u64 v[158:159], s[72:73], 0, v[136:137]
	s_add_i32 m0, s28, 0xe000
	s_nop 0
	global_load_lds_dwordx4 v[158:159], off
	s_waitcnt vmcnt(24)
	s_cmp_eq_u32 s83, s98
	s_cbranch_scc1 .Lrx_dn_0
	s_waitcnt vmcnt(8)
; #define PG8_STAGE(bufoff, gbase, voff) do { _Pragma("unroll") for (int _i = 0; _i < 2; ++_i) \
;         __builtin_amdgcn_global_load_lds((const unsigned*)((const char*)(gbase) + (voff)[_i]), (PG8_LAS unsigned*)(lds + (bufoff) + ldsw + _i * 8192), 16, 0, 0); } while (0)
; #define PG8_LDA(dst, b, h) do { _Pragma("unroll") for (int m = 0; m < 4; ++m) _Pragma("unroll") for (int k = 0; k < 2; ++k) dst[m][k] = *(const PG8_LAS bf16x8*)(lds + PG8_SA(b, h) + aoff + m * 2048 + k * 1024); } while (0)
; #define PG8_MMA(ai, bj, At, Bt) do { __builtin_amdgcn_s_setprio(1); _Pragma("unroll") for (int m = 0; m < 4; ++m) _Pragma("unroll") for (int n = 0; n < 2; ++n) _Pragma("unroll") for (int k = 0; k < 2; ++k) \
;         acc[ai][bj][m][n] = __builtin_amdgcn_mfma_f32_16x16x32_bf16(Bt[n][k], At[m][k], acc[ai][bj][m][n], 0, 0, 0); __builtin_amdgcn_s_setprio(0); } while (0)
; #define PG8_WAIT_V(n) asm volatile("s_waitcnt vmcnt(" #n ")" ::: "memory")
; #define PG8_WAIT_L(n) asm volatile("s_waitcnt lgkmcnt(" #n ")" ::: "memory")
; #define PG8_BAR __builtin_amdgcn_s_barrier()
; #define PG8_SCHED __builtin_amdgcn_sched_barrier(0)
; template <class Epi, class Sched, bool ALIGN_EPI = false, bool SP2 = false>
; __device__ __forceinline__ void gemm_phase(PG8_LAS unsigned char* lds, const Gemm g, const Sched& S, const Epi& E) {
;     ...
;             PG8_WAIT_V(8); PG8_WAIT_L(0); PG8_BAR; PG8_MMA(0, 0, At, B0); PG8_MMA(0, 1, At, B1); PG8_BAR; PG8_SCHED;
;             PG8_LDA(At, 0, 1); PG8_STAGE(PG8_SB(0, 0), b2, voffB); PG8_STAGE(PG8_SB(0, 1), b2 + hstep, voffB); PG8_STAGE(PG8_SA(0, 0), a2, voffA);
;             PG8_WAIT_V(8); PG8_WAIT_L(0); PG8_BAR; PG8_MMA(1, 0, At, B0); PG8_MMA(1, 1, At, B1); PG8_BAR; PG8_SCHED;
.Lrx_dn_0:
	s_waitcnt lgkmcnt(0)
	s_barrier
	s_setprio 1
	s_waitcnt lgkmcnt(0)
	v_mfma_f32_16x16x32_bf16 v[124:127], v[142:145], v[180:183], v[124:127]
	v_mfma_f32_16x16x32_bf16 v[120:123], v[150:153], v[180:183], v[120:123]
	v_mfma_f32_16x16x32_bf16 v[116:119], v[142:145], v[188:191], v[116:119]
	v_mfma_f32_16x16x32_bf16 v[112:115], v[150:153], v[188:191], v[112:115]
	v_mfma_f32_16x16x32_bf16 v[100:103], v[142:145], v[196:199], v[100:103]
	v_mfma_f32_16x16x32_bf16 v[96:99], v[150:153], v[196:199], v[96:99]
	v_mfma_f32_16x16x32_bf16 v[84:87], v[142:145], v[226:229], v[84:87]
	v_mfma_f32_16x16x32_bf16 v[80:83], v[150:153], v[226:229], v[80:83]
	v_mfma_f32_16x16x32_bf16 v[124:127], v[146:149], v[184:187], v[124:127]
	v_mfma_f32_16x16x32_bf16 v[120:123], v[154:157], v[184:187], v[120:123]
	v_mfma_f32_16x16x32_bf16 v[116:119], v[146:149], v[192:195], v[116:119]
	v_mfma_f32_16x16x32_bf16 v[112:115], v[154:157], v[192:195], v[112:115]
	v_mfma_f32_16x16x32_bf16 v[100:103], v[146:149], v[222:225], v[100:103]
	v_mfma_f32_16x16x32_bf16 v[96:99], v[154:157], v[222:225], v[96:99]
	v_mfma_f32_16x16x32_bf16 v[84:87], v[146:149], v[230:233], v[84:87]
	v_mfma_f32_16x16x32_bf16 v[80:83], v[154:157], v[230:233], v[80:83]
	s_setprio 0
	s_setprio 1
	v_mfma_f32_16x16x32_bf16 v[108:111], v[164:167], v[180:183], v[108:111]
	v_mfma_f32_16x16x32_bf16 v[104:107], v[172:175], v[180:183], v[104:107]
	v_mfma_f32_16x16x32_bf16 v[92:95], v[164:167], v[188:191], v[92:95]
	v_mfma_f32_16x16x32_bf16 v[88:91], v[172:175], v[188:191], v[88:91]
	v_mfma_f32_16x16x32_bf16 v[76:79], v[164:167], v[196:199], v[76:79]
	v_mfma_f32_16x16x32_bf16 v[72:75], v[172:175], v[196:199], v[72:75]
	v_mfma_f32_16x16x32_bf16 v[68:71], v[164:167], v[226:229], v[68:71]
	v_mfma_f32_16x16x32_bf16 v[64:67], v[172:175], v[226:229], v[64:67]
	v_mfma_f32_16x16x32_bf16 v[108:111], v[168:171], v[184:187], v[108:111]
	v_mfma_f32_16x16x32_bf16 v[104:107], v[176:179], v[184:187], v[104:107]
	v_mfma_f32_16x16x32_bf16 v[92:95], v[168:171], v[192:195], v[92:95]
	v_mfma_f32_16x16x32_bf16 v[88:91], v[176:179], v[192:195], v[88:91]
	v_mfma_f32_16x16x32_bf16 v[76:79], v[168:171], v[222:225], v[76:79]
	v_mfma_f32_16x16x32_bf16 v[72:75], v[176:179], v[222:225], v[72:75]
	v_mfma_f32_16x16x32_bf16 v[68:71], v[168:171], v[230:233], v[68:71]
	v_mfma_f32_16x16x32_bf16 v[64:67], v[176:179], v[230:233], v[64:67]
	s_setprio 0
	s_barrier
	s_add_i32 s72, s84, s24
	v_lshl_add_u64 v[158:159], s[52:53], 0, v[160:161]
	s_mov_b32 m0, s72
	ds_read_b128 v[180:183], v141 offset:16384
	ds_read_b128 v[184:187], v141 offset:17408
	ds_read_b128 v[188:191], v141 offset:18432
	ds_read_b128 v[192:195], v141 offset:19456
	ds_read_b128 v[196:199], v141 offset:20480
	ds_read_b128 v[222:225], v141 offset:21504
	ds_read_b128 v[226:229], v141 offset:22528
	ds_read_b128 v[230:233], v141 offset:23552
	global_load_lds_dwordx4 v[158:159], off
	s_add_i32 m0, s72, 0x2000
	s_add_u32 s72, s52, 0x160000
	v_lshl_add_u64 v[200:201], s[52:53], 0, v[128:129]
	s_addc_u32 s73, s53, 0
	s_add_i32 s84, s85, s24
	global_load_lds_dwordx4 v[200:201], off
	v_lshl_add_u64 v[234:235], s[72:73], 0, v[160:161]
	s_mov_b32 m0, s84
	v_lshl_add_u64 v[236:237], s[56:57], 0, v[130:131]
	global_load_lds_dwordx4 v[234:235], off
	v_lshl_add_u64 v[234:235], s[72:73], 0, v[128:129]
	s_add_i32 m0, s84, 0x2000
	s_nop 0
	global_load_lds_dwordx4 v[234:235], off
	v_lshl_add_u64 v[234:235], s[56:57], 0, v[132:133]
	s_mov_b32 m0, s28
	s_nop 0
	global_load_lds_dwordx4 v[234:235], off
	s_mov_b32 m0, s29
	s_nop 0
	global_load_lds_dwordx4 v[236:237], off
	s_waitcnt vmcnt(24)
	s_cmp_eq_u32 s83, s98
	s_cbranch_scc1 .Lrx_dn_1
	s_waitcnt vmcnt(8)
.Lrx_dn_1:
	s_waitcnt lgkmcnt(0)
	s_barrier
	s_setprio 1
	s_waitcnt lgkmcnt(0)
	v_mfma_f32_16x16x32_bf16 v[60:63], v[142:145], v[180:183], v[60:63]
	v_mfma_f32_16x16x32_bf16 v[56:59], v[150:153], v[180:183], v[56:59]
	v_mfma_f32_16x16x32_bf16 v[52:55], v[142:145], v[188:191], v[52:55]
	v_mfma_f32_16x16x32_bf16 v[48:51], v[150:153], v[188:191], v[48:51]
	v_mfma_f32_16x16x32_bf16 v[36:39], v[142:145], v[196:199], v[36:39]
	v_mfma_f32_16x16x32_bf16 v[32:35], v[150:153], v[196:199], v[32:35]
	v_mfma_f32_16x16x32_bf16 v[20:23], v[142:145], v[226:229], v[20:23]
	v_mfma_f32_16x16x32_bf16 v[16:19], v[150:153], v[226:229], v[16:19]
	v_mfma_f32_16x16x32_bf16 v[60:63], v[146:149], v[184:187], v[60:63]
	v_mfma_f32_16x16x32_bf16 v[56:59], v[154:157], v[184:187], v[56:59]
	v_mfma_f32_16x16x32_bf16 v[52:55], v[146:149], v[192:195], v[52:55]
	v_mfma_f32_16x16x32_bf16 v[48:51], v[154:157], v[192:195], v[48:51]
	v_mfma_f32_16x16x32_bf16 v[36:39], v[146:149], v[222:225], v[36:39]
	v_mfma_f32_16x16x32_bf16 v[32:35], v[154:157], v[222:225], v[32:35]
	v_mfma_f32_16x16x32_bf16 v[20:23], v[146:149], v[230:233], v[20:23]
	v_mfma_f32_16x16x32_bf16 v[16:19], v[154:157], v[230:233], v[16:19]
	s_setprio 0
	s_setprio 1
	v_mfma_f32_16x16x32_bf16 v[44:47], v[164:167], v[180:183], v[44:47]
	v_mfma_f32_16x16x32_bf16 v[40:43], v[172:175], v[180:183], v[40:43]
	v_mfma_f32_16x16x32_bf16 v[28:31], v[164:167], v[188:191], v[28:31]
	v_mfma_f32_16x16x32_bf16 v[24:27], v[172:175], v[188:191], v[24:27]
	v_mfma_f32_16x16x32_bf16 v[12:15], v[164:167], v[196:199], v[12:15]
	v_mfma_f32_16x16x32_bf16 v[8:11], v[172:175], v[196:199], v[8:11]
	v_mfma_f32_16x16x32_bf16 v[4:7], v[164:167], v[226:229], v[4:7]
	v_mfma_f32_16x16x32_bf16 v[0:3], v[172:175], v[226:229], v[0:3]
	v_mfma_f32_16x16x32_bf16 v[44:47], v[168:171], v[184:187], v[44:47]
	v_mfma_f32_16x16x32_bf16 v[40:43], v[176:179], v[184:187], v[40:43]
	v_mfma_f32_16x16x32_bf16 v[28:31], v[168:171], v[192:195], v[28:31]
	v_mfma_f32_16x16x32_bf16 v[24:27], v[176:179], v[192:195], v[24:27]
	v_mfma_f32_16x16x32_bf16 v[12:15], v[168:171], v[222:225], v[12:15]
	v_mfma_f32_16x16x32_bf16 v[8:11], v[176:179], v[222:225], v[8:11]
	v_mfma_f32_16x16x32_bf16 v[4:7], v[168:171], v[230:233], v[4:7]
	v_mfma_f32_16x16x32_bf16 v[0:3], v[176:179], v[230:233], v[0:3]
	s_setprio 0
	s_barrier
; #define PG8_STAGE(bufoff, gbase, voff) do { _Pragma("unroll") for (int _i = 0; _i < 2; ++_i) \
;         __builtin_amdgcn_global_load_lds((const unsigned*)((const char*)(gbase) + (voff)[_i]), (PG8_LAS unsigned*)(lds + (bufoff) + ldsw + _i * 8192), 16, 0, 0); } while (0)
; #define PG8_LDA(dst, b, h) do { _Pragma("unroll") for (int m = 0; m < 4; ++m) _Pragma("unroll") for (int k = 0; k < 2; ++k) dst[m][k] = *(const PG8_LAS bf16x8*)(lds + PG8_SA(b, h) + aoff + m * 2048 + k * 1024); } while (0)
; #define PG8_LDB(dst, b, h) do { _Pragma("unroll") for (int n = 0; n < 2; ++n) _Pragma("unroll") for (int k = 0; k < 2; ++k) dst[n][k] = *(const PG8_LAS bf16x8*)(lds + PG8_SB(b, h) + boff + n * 2048 + k * 1024); } while (0)
; #define PG8_MMA(ai, bj, At, Bt) do { __builtin_amdgcn_s_setprio(1); _Pragma("unroll") for (int m = 0; m < 4; ++m) _Pragma("unroll") for (int n = 0; n < 2; ++n) _Pragma("unroll") for (int k = 0; k < 2; ++k) \
;         acc[ai][bj][m][n] = __builtin_amdgcn_mfma_f32_16x16x32_bf16(Bt[n][k], At[m][k], acc[ai][bj][m][n], 0, 0, 0); __builtin_amdgcn_s_setprio(0); } while (0)
; #define PG8_WAIT_V(n) asm volatile("s_waitcnt vmcnt(" #n ")" ::: "memory")
; #define PG8_WAIT_L(n) asm volatile("s_waitcnt lgkmcnt(" #n ")" ::: "memory")
; #define PG8_BAR __builtin_amdgcn_s_barrier()
; #define PG8_SCHED __builtin_amdgcn_sched_barrier(0)
; template <class Epi, class Sched, bool ALIGN_EPI = false, bool SP2 = false>
; __device__ __forceinline__ void gemm_phase(PG8_LAS unsigned char* lds, const Gemm g, const Sched& S, const Epi& E) {
;     ...
;             PG8_LDB(B0, 1, 0); PG8_LDB(B1, 1, 1); PG8_SCHED; PG8_LDA(At, 1, 0); PG8_STAGE(PG8_SA(0, 1), a2 + hstep, voffA);
;             PG8_WAIT_V(8); PG8_WAIT_L(0); PG8_BAR; PG8_MMA(0, 0, At, B0); PG8_MMA(0, 1, At, B1); PG8_BAR; PG8_SCHED;
	s_add_i32 s72, 0, 0x18000
	s_add_i32 s73, 0, 0x1c000
	v_add_u32_e32 v154, s72, v139
	v_add_u32_e32 v163, s73, v139
	ds_read_b128 v[142:145], v154
	ds_read_b128 v[146:149], v154 offset:1024
	ds_read_b128 v[150:153], v154 offset:2048
	ds_read_b128 v[154:157], v154 offset:3072
	ds_read_b128 v[164:167], v163
	ds_read_b128 v[168:171], v163 offset:1024
	ds_read_b128 v[172:175], v163 offset:2048
	ds_read_b128 v[176:179], v163 offset:3072
	s_add_u32 s56, s56, 0x160000
	s_addc_u32 s57, s57, 0
	s_mov_b32 m0, s59
	v_lshl_add_u64 v[238:239], s[56:57], 0, v[132:133]
	ds_read_b128 v[180:183], v141 offset:32768
	ds_read_b128 v[184:187], v141 offset:33792
	ds_read_b128 v[188:191], v141 offset:34816
	ds_read_b128 v[192:195], v141 offset:35840
	ds_read_b128 v[196:199], v141 offset:36864
	ds_read_b128 v[222:225], v141 offset:37888
	ds_read_b128 v[226:229], v141 offset:38912
	ds_read_b128 v[230:233], v141 offset:39936
	global_load_lds_dwordx4 v[238:239], off
	v_lshl_add_u64 v[238:239], s[56:57], 0, v[130:131]
	s_mov_b32 m0, s63
	s_nop 0
	global_load_lds_dwordx4 v[238:239], off
	s_waitcnt vmcnt(8)
	s_waitcnt lgkmcnt(0)
	s_barrier
	s_setprio 1
	s_waitcnt lgkmcnt(0)
	v_mfma_f32_16x16x32_bf16 v[124:127], v[142:145], v[180:183], v[124:127]
	v_mfma_f32_16x16x32_bf16 v[120:123], v[150:153], v[180:183], v[120:123]
	v_mfma_f32_16x16x32_bf16 v[116:119], v[142:145], v[188:191], v[116:119]
	v_mfma_f32_16x16x32_bf16 v[112:115], v[150:153], v[188:191], v[112:115]
	v_mfma_f32_16x16x32_bf16 v[100:103], v[142:145], v[196:199], v[100:103]
	v_mfma_f32_16x16x32_bf16 v[96:99], v[150:153], v[196:199], v[96:99]
	v_mfma_f32_16x16x32_bf16 v[84:87], v[142:145], v[226:229], v[84:87]
	v_mfma_f32_16x16x32_bf16 v[80:83], v[150:153], v[226:229], v[80:83]
	v_mfma_f32_16x16x32_bf16 v[124:127], v[146:149], v[184:187], v[124:127]
	v_mfma_f32_16x16x32_bf16 v[120:123], v[154:157], v[184:187], v[120:123]
	v_mfma_f32_16x16x32_bf16 v[116:119], v[146:149], v[192:195], v[116:119]
	v_mfma_f32_16x16x32_bf16 v[112:115], v[154:157], v[192:195], v[112:115]
	v_mfma_f32_16x16x32_bf16 v[100:103], v[146:149], v[222:225], v[100:103]
	v_mfma_f32_16x16x32_bf16 v[96:99], v[154:157], v[222:225], v[96:99]
	v_mfma_f32_16x16x32_bf16 v[84:87], v[146:149], v[230:233], v[84:87]
	v_mfma_f32_16x16x32_bf16 v[80:83], v[154:157], v[230:233], v[80:83]
	s_setprio 0
	s_setprio 1
	v_mfma_f32_16x16x32_bf16 v[108:111], v[164:167], v[180:183], v[108:111]
	v_mfma_f32_16x16x32_bf16 v[104:107], v[172:175], v[180:183], v[104:107]
	v_mfma_f32_16x16x32_bf16 v[92:95], v[164:167], v[188:191], v[92:95]
	v_mfma_f32_16x16x32_bf16 v[88:91], v[172:175], v[188:191], v[88:91]
	v_mfma_f32_16x16x32_bf16 v[76:79], v[164:167], v[196:199], v[76:79]
	v_mfma_f32_16x16x32_bf16 v[72:75], v[172:175], v[196:199], v[72:75]
	v_mfma_f32_16x16x32_bf16 v[68:71], v[164:167], v[226:229], v[68:71]
	v_mfma_f32_16x16x32_bf16 v[64:67], v[172:175], v[226:229], v[64:67]
	v_mfma_f32_16x16x32_bf16 v[108:111], v[168:171], v[184:187], v[108:111]
	v_mfma_f32_16x16x32_bf16 v[104:107], v[176:179], v[184:187], v[104:107]
	v_mfma_f32_16x16x32_bf16 v[92:95], v[168:171], v[192:195], v[92:95]
	v_mfma_f32_16x16x32_bf16 v[88:91], v[176:179], v[192:195], v[88:91]
	v_mfma_f32_16x16x32_bf16 v[76:79], v[168:171], v[222:225], v[76:79]
	v_mfma_f32_16x16x32_bf16 v[72:75], v[176:179], v[222:225], v[72:75]
	v_mfma_f32_16x16x32_bf16 v[68:71], v[168:171], v[230:233], v[68:71]
	v_mfma_f32_16x16x32_bf16 v[64:67], v[176:179], v[230:233], v[64:67]
	s_setprio 0
	s_barrier
; #define PG8_STAGE(bufoff, gbase, voff) do { _Pragma("unroll") for (int _i = 0; _i < 2; ++_i) \
;         __builtin_amdgcn_global_load_lds((const unsigned*)((const char*)(gbase) + (voff)[_i]), (PG8_LAS unsigned*)(lds + (bufoff) + ldsw + _i * 8192), 16, 0, 0); } while (0)
; #define PG8_LDA(dst, b, h) do { _Pragma("unroll") for (int m = 0; m < 4; ++m) _Pragma("unroll") for (int k = 0; k < 2; ++k) dst[m][k] = *(const PG8_LAS bf16x8*)(lds + PG8_SA(b, h) + aoff + m * 2048 + k * 1024); } while (0)
; #define PG8_MMA(ai, bj, At, Bt) do { __builtin_amdgcn_s_setprio(1); _Pragma("unroll") for (int m = 0; m < 4; ++m) _Pragma("unroll") for (int n = 0; n < 2; ++n) _Pragma("unroll") for (int k = 0; k < 2; ++k) \
;         acc[ai][bj][m][n] = __builtin_amdgcn_mfma_f32_16x16x32_bf16(Bt[n][k], At[m][k], acc[ai][bj][m][n], 0, 0, 0); __builtin_amdgcn_s_setprio(0); } while (0)
; #define PG8_WAIT_V(n) asm volatile("s_waitcnt vmcnt(" #n ")" ::: "memory")
; #define PG8_WAIT_L(n) asm volatile("s_waitcnt lgkmcnt(" #n ")" ::: "memory")
; #define PG8_BAR __builtin_amdgcn_s_barrier()
; #define PG8_SCHED __builtin_amdgcn_sched_barrier(0)
; template <class Epi, class Sched, bool ALIGN_EPI = false, bool SP2 = false>
; __device__ __forceinline__ void gemm_phase(PG8_LAS unsigned char* lds, const Gemm g, const Sched& S, const Epi& E) {
;     ...
;             PG8_LDA(At, 1, 1); PG8_STAGE(PG8_SB(1, 0), b3, voffB); PG8_STAGE(PG8_SB(1, 1), b3 + hstep, voffB); PG8_STAGE(PG8_SA(1, 0), a3, voffA);
;             PG8_WAIT_V(8); PG8_WAIT_L(0); PG8_BAR; PG8_MMA(1, 0, At, B0); PG8_MMA(1, 1, At, B1); PG8_BAR; PG8_SCHED;
	s_add_i32 s56, s72, s24
	v_lshl_add_u64 v[158:159], v[158:159], 0, s[30:31]
	s_mov_b32 m0, s56
	ds_read_b128 v[180:183], v141 offset:49152
	ds_read_b128 v[184:187], v141 offset:50176
	ds_read_b128 v[188:191], v141 offset:51200
	ds_read_b128 v[192:195], v141 offset:52224
	ds_read_b128 v[196:199], v141 offset:53248
	ds_read_b128 v[222:225], v141 offset:54272
	ds_read_b128 v[226:229], v141 offset:55296
	ds_read_b128 v[230:233], v141 offset:56320
	global_load_lds_dwordx4 v[158:159], off
	s_add_i32 m0, s56, 0x2000
	s_add_u32 s52, s52, 0x160080
	v_lshl_add_u64 v[158:159], v[200:201], 0, s[30:31]
	s_addc_u32 s53, s53, 0
	s_add_i32 s56, s73, s24
	global_load_lds_dwordx4 v[158:159], off
	v_lshl_add_u64 v[158:159], s[52:53], 0, v[160:161]
	s_mov_b32 m0, s56
	s_nop 0
	global_load_lds_dwordx4 v[158:159], off
	v_lshl_add_u64 v[158:159], s[52:53], 0, v[128:129]
	s_add_i32 m0, s56, 0x2000
	s_nop 0
	global_load_lds_dwordx4 v[158:159], off
	v_lshl_add_u64 v[158:159], v[234:235], 0, s[30:31]
	s_mov_b32 m0, s74
	s_nop 0
	global_load_lds_dwordx4 v[158:159], off
	v_lshl_add_u64 v[158:159], v[236:237], 0, s[30:31]
	s_mov_b32 m0, s75
	s_nop 0
	global_load_lds_dwordx4 v[158:159], off
	s_waitcnt vmcnt(8)
	s_waitcnt lgkmcnt(0)
	s_barrier
	s_setprio 1
	s_waitcnt lgkmcnt(0)
	v_mfma_f32_16x16x32_bf16 v[60:63], v[142:145], v[180:183], v[60:63]
	v_mfma_f32_16x16x32_bf16 v[56:59], v[150:153], v[180:183], v[56:59]
	v_mfma_f32_16x16x32_bf16 v[52:55], v[142:145], v[188:191], v[52:55]
	v_mfma_f32_16x16x32_bf16 v[48:51], v[150:153], v[188:191], v[48:51]
	v_mfma_f32_16x16x32_bf16 v[36:39], v[142:145], v[196:199], v[36:39]
	v_mfma_f32_16x16x32_bf16 v[32:35], v[150:153], v[196:199], v[32:35]
	v_mfma_f32_16x16x32_bf16 v[20:23], v[142:145], v[226:229], v[20:23]
	v_mfma_f32_16x16x32_bf16 v[16:19], v[150:153], v[226:229], v[16:19]
	v_mfma_f32_16x16x32_bf16 v[60:63], v[146:149], v[184:187], v[60:63]
	v_mfma_f32_16x16x32_bf16 v[56:59], v[154:157], v[184:187], v[56:59]
	v_mfma_f32_16x16x32_bf16 v[52:55], v[146:149], v[192:195], v[52:55]
	v_mfma_f32_16x16x32_bf16 v[48:51], v[154:157], v[192:195], v[48:51]
	v_mfma_f32_16x16x32_bf16 v[36:39], v[146:149], v[222:225], v[36:39]
	v_mfma_f32_16x16x32_bf16 v[32:35], v[154:157], v[222:225], v[32:35]
	v_mfma_f32_16x16x32_bf16 v[20:23], v[146:149], v[230:233], v[20:23]
	v_mfma_f32_16x16x32_bf16 v[16:19], v[154:157], v[230:233], v[16:19]
	s_setprio 0
	s_setprio 1
	v_mfma_f32_16x16x32_bf16 v[44:47], v[164:167], v[180:183], v[44:47]
	v_mfma_f32_16x16x32_bf16 v[40:43], v[172:175], v[180:183], v[40:43]
	v_mfma_f32_16x16x32_bf16 v[28:31], v[164:167], v[188:191], v[28:31]
	v_mfma_f32_16x16x32_bf16 v[24:27], v[172:175], v[188:191], v[24:27]
	v_mfma_f32_16x16x32_bf16 v[12:15], v[164:167], v[196:199], v[12:15]
	v_mfma_f32_16x16x32_bf16 v[8:11], v[172:175], v[196:199], v[8:11]
	v_mfma_f32_16x16x32_bf16 v[4:7], v[164:167], v[226:229], v[4:7]
	v_mfma_f32_16x16x32_bf16 v[0:3], v[172:175], v[226:229], v[0:3]
	v_mfma_f32_16x16x32_bf16 v[44:47], v[168:171], v[184:187], v[44:47]
	v_mfma_f32_16x16x32_bf16 v[40:43], v[176:179], v[184:187], v[40:43]
	v_mfma_f32_16x16x32_bf16 v[28:31], v[168:171], v[192:195], v[28:31]
	v_mfma_f32_16x16x32_bf16 v[24:27], v[176:179], v[192:195], v[24:27]
	v_mfma_f32_16x16x32_bf16 v[12:15], v[168:171], v[222:225], v[12:15]
	v_mfma_f32_16x16x32_bf16 v[8:11], v[176:179], v[222:225], v[8:11]
	v_mfma_f32_16x16x32_bf16 v[4:7], v[168:171], v[230:233], v[4:7]
	v_mfma_f32_16x16x32_bf16 v[0:3], v[176:179], v[230:233], v[0:3]
	s_setprio 0
	s_barrier
	s_add_i32 s83, s83, 2
	s_add_u32 s81, s81, 0x100
	s_addc_u32 s82, s82, 0
	s_cmpk_gt_u32 s83, 0x55
	s_mov_b64 s[72:73], s[4:5]
	s_cbranch_scc0 .LBB0_52
	s_and_b64 vcc, exec, s[42:43]
	s_cbranch_vccz .LBB0_55
	s_barrier

;     __host__ __device__ bool next(int i, Unit& u) const { if (!base.next(i >> 1, u)) return false; if (i & 1) { u.pm += 64; u.pn += 8; } return true; }
; #define PG8_STAGE(bufoff, gbase, voff) do { _Pragma("unroll") for (int _i = 0; _i < 2; ++_i) \
;         __builtin_amdgcn_global_load_lds((const unsigned*)((const char*)(gbase) + (voff)[_i]), (PG8_LAS unsigned*)(lds + (bufoff) + ldsw + _i * 8192), 16, 0, 0); } while (0)
; #define PG8_LDA(dst, b, h) do { _Pragma("unroll") for (int m = 0; m < 4; ++m) _Pragma("unroll") for (int k = 0; k < 2; ++k) dst[m][k] = *(const PG8_LAS bf16x8*)(lds + PG8_SA(b, h) + aoff + m * 2048 + k * 1024); } while (0)
; #define PG8_LDB(dst, b, h) do { _Pragma("unroll") for (int n = 0; n < 2; ++n) _Pragma("unroll") for (int k = 0; k < 2; ++k) dst[n][k] = *(const PG8_LAS bf16x8*)(lds + PG8_SB(b, h) + boff + n * 2048 + k * 1024); } while (0)
; #define PG8_SCHED __builtin_amdgcn_sched_barrier(0)
; template <class Epi, class Sched, bool ALIGN_EPI = false, bool SP2 = false>
; __device__ __forceinline__ void gemm_phase(PG8_LAS unsigned char* lds, const Gemm g, const Sched& S, const Epi& E) {
;     ...
;         const bool has_next = S.next(ui + 1, nxt);
;         const char* nA = has_next ? (const char*)g.A + (size_t)nxt.pm * tstep : cA; const char* nB = has_next ? (const char*)g.Bt + (size_t)nxt.pn * tstep : cB;
;         for (int t = 0; t < nt; t += 2) {
;             const bool last = (t == nt - 2);
;             const char* a1 = cA + (size_t)(t + 1) * kstep;
;             const char* a2 = last ? nA : cA + (size_t)(t + 2) * kstep; const char* b2 = last ? nB : cB + (size_t)(t + 2) * kstep;
;             const char* a3 = a2 + kstep; const char* b3 = b2 + kstep;
;             if (last && has_next) S.a_ready(nxt);
;             if constexpr (SP2) {
;             PG8_LDB(B0, 0, 0); PG8_LDB(B1, 0, 1); PG8_SCHED; PG8_LDA(At, 0, 0); PG8_STAGE(PG8_SA(1, 1), a1 + hstep, voffA);
.LBB0_85:
	s_bitcmp0_b32 s7, 0
	s_cselect_b64 s[28:29], -1, 0
	s_and_b64 s[28:29], s[28:29], s[44:45]
	s_add_i32 s7, s14, 64
	s_add_i32 s15, s42, 8
	s_and_b64 s[28:29], s[28:29], exec
	s_cselect_b32 s14, s7, s14
	s_cselect_b32 s42, s15, s42
	s_ashr_i32 s15, s14, 31
	s_lshl_b64 s[28:29], s[14:15], 19
	s_add_u32 s54, s56, s28
	s_addc_u32 s55, s57, s29
	s_and_b64 s[28:29], s[44:45], exec
	s_cselect_b32 s7, s55, s53
	s_cselect_b32 s15, s54, s52
	s_ashr_i32 s43, s42, 31
	s_lshl_b64 s[28:29], s[42:43], 19
	s_add_u32 s78, s0, s28
	s_addc_u32 s79, s1, s29
	s_and_b64 s[28:29], s[44:45], exec
	s_cselect_b32 s24, s79, s5
	s_cselect_b32 s28, s78, s4
	s_add_u32 s82, s52, 0x40080
	s_addc_u32 s83, s53, 0
	s_add_u32 s29, s4, 0x100
	v_mov_b32_e32 v0, 0
	s_addc_u32 s43, s5, 0
	s_mov_b32 s87, -2
	s_cmp_gt_i32 s86, 1
	s_cselect_b32 s62, -2, 0x7fffffff
	v_mov_b32_e32 v1, v0
	v_mov_b32_e32 v2, v0
	v_mov_b32_e32 v3, v0
	v_mov_b32_e32 v4, v0
	v_mov_b32_e32 v5, v0
	v_mov_b32_e32 v6, v0
	v_mov_b32_e32 v7, v0
	v_mov_b32_e32 v16, v0
	v_mov_b32_e32 v17, v0
	v_mov_b32_e32 v18, v0
	v_mov_b32_e32 v19, v0
	v_mov_b32_e32 v20, v0
	v_mov_b32_e32 v21, v0
	v_mov_b32_e32 v22, v0
	v_mov_b32_e32 v23, v0
	v_mov_b32_e32 v32, v0
	v_mov_b32_e32 v33, v0
	v_mov_b32_e32 v34, v0
	v_mov_b32_e32 v35, v0
	v_mov_b32_e32 v36, v0
	v_mov_b32_e32 v37, v0
	v_mov_b32_e32 v38, v0
	v_mov_b32_e32 v39, v0
	v_mov_b32_e32 v48, v0
	v_mov_b32_e32 v49, v0
	v_mov_b32_e32 v50, v0
	v_mov_b32_e32 v51, v0
	v_mov_b32_e32 v52, v0
	v_mov_b32_e32 v53, v0
	v_mov_b32_e32 v54, v0
	v_mov_b32_e32 v55, v0
	v_mov_b32_e32 v8, v0
	v_mov_b32_e32 v9, v0
	v_mov_b32_e32 v10, v0
	v_mov_b32_e32 v11, v0
	v_mov_b32_e32 v12, v0
	v_mov_b32_e32 v13, v0
	v_mov_b32_e32 v14, v0
	v_mov_b32_e32 v15, v0
	v_mov_b32_e32 v24, v0
	v_mov_b32_e32 v25, v0
	v_mov_b32_e32 v26, v0
	v_mov_b32_e32 v27, v0
	v_mov_b32_e32 v28, v0
	v_mov_b32_e32 v29, v0
	v_mov_b32_e32 v30, v0
	v_mov_b32_e32 v31, v0
	v_mov_b32_e32 v40, v0
	v_mov_b32_e32 v41, v0
	v_mov_b32_e32 v42, v0
	v_mov_b32_e32 v43, v0
	v_mov_b32_e32 v44, v0
	v_mov_b32_e32 v45, v0
	v_mov_b32_e32 v46, v0
	v_mov_b32_e32 v47, v0
	v_mov_b32_e32 v56, v0
	v_mov_b32_e32 v57, v0
	v_mov_b32_e32 v58, v0
	v_mov_b32_e32 v59, v0
	v_mov_b32_e32 v60, v0
	v_mov_b32_e32 v61, v0
	v_mov_b32_e32 v62, v0
	v_mov_b32_e32 v63, v0
	v_mov_b32_e32 v64, v0
	v_mov_b32_e32 v65, v0
	v_mov_b32_e32 v66, v0
	v_mov_b32_e32 v67, v0
	v_mov_b32_e32 v68, v0
	v_mov_b32_e32 v69, v0
	v_mov_b32_e32 v70, v0
	v_mov_b32_e32 v71, v0
	v_mov_b32_e32 v80, v0
	v_mov_b32_e32 v81, v0
	v_mov_b32_e32 v82, v0
	v_mov_b32_e32 v83, v0
	v_mov_b32_e32 v84, v0
	v_mov_b32_e32 v85, v0
	v_mov_b32_e32 v86, v0
	v_mov_b32_e32 v87, v0
	v_mov_b32_e32 v96, v0
	v_mov_b32_e32 v97, v0
	v_mov_b32_e32 v98, v0
	v_mov_b32_e32 v99, v0
	v_mov_b32_e32 v100, v0
	v_mov_b32_e32 v101, v0
	v_mov_b32_e32 v102, v0
	v_mov_b32_e32 v103, v0
	v_mov_b32_e32 v112, v0
	v_mov_b32_e32 v113, v0
	v_mov_b32_e32 v114, v0
	v_mov_b32_e32 v115, v0
	v_mov_b32_e32 v116, v0
	v_mov_b32_e32 v117, v0
	v_mov_b32_e32 v118, v0
	v_mov_b32_e32 v119, v0
	v_mov_b32_e32 v72, v0
	v_mov_b32_e32 v73, v0
	v_mov_b32_e32 v74, v0
	v_mov_b32_e32 v75, v0
	v_mov_b32_e32 v76, v0
	v_mov_b32_e32 v77, v0
	v_mov_b32_e32 v78, v0
	v_mov_b32_e32 v79, v0
	v_mov_b32_e32 v88, v0
	v_mov_b32_e32 v89, v0
	v_mov_b32_e32 v90, v0
	v_mov_b32_e32 v91, v0
	v_mov_b32_e32 v92, v0
	v_mov_b32_e32 v93, v0
	v_mov_b32_e32 v94, v0
	v_mov_b32_e32 v95, v0
	v_mov_b32_e32 v104, v0
	v_mov_b32_e32 v105, v0
	v_mov_b32_e32 v106, v0
	v_mov_b32_e32 v107, v0
	v_mov_b32_e32 v108, v0
	v_mov_b32_e32 v109, v0
	v_mov_b32_e32 v110, v0
	v_mov_b32_e32 v111, v0
	v_mov_b32_e32 v120, v0
	v_mov_b32_e32 v121, v0
	v_mov_b32_e32 v122, v0
	v_mov_b32_e32 v123, v0
	v_mov_b32_e32 v124, v0
	v_mov_b32_e32 v125, v0
	v_mov_b32_e32 v126, v0
	v_mov_b32_e32 v127, v0
.LBB0_86:
	s_add_u32 s4, s82, 0xfffc0080
	s_addc_u32 s5, s83, -1
	s_add_i32 s88, 0, 0x10000
	s_cmp_eq_u32 s87, 12
	s_cselect_b32 s53, s7, s5
	s_cselect_b32 s52, s15, s4
	v_add_u32_e32 v144, s88, v147
	s_cselect_b32 s5, s24, s43
	s_cselect_b32 s4, s28, s29
	s_add_i32 s90, 0, 0x14000
	ds_read_b128 v[140:143], v144
	ds_read_b128 v[150:153], v144 offset:1024
	ds_read_b128 v[154:157], v144 offset:2048
	ds_read_b128 v[164:167], v144 offset:3072
	v_add_u32_e32 v144, s90, v147
	ds_read_b128 v[168:171], v144
	ds_read_b128 v[172:175], v144 offset:1024
	ds_read_b128 v[176:179], v144 offset:2048
	ds_read_b128 v[180:183], v144 offset:3072
	v_lshl_add_u64 v[144:145], s[82:83], 0, v[136:137]
	s_add_i32 m0, s63, 0xc000
	ds_read_b128 v[184:187], v149
	ds_read_b128 v[188:191], v149 offset:1024
	ds_read_b128 v[192:195], v149 offset:2048
	ds_read_b128 v[196:199], v149 offset:3072
	ds_read_b128 v[222:225], v149 offset:4096
	ds_read_b128 v[226:229], v149 offset:5120
	ds_read_b128 v[230:233], v149 offset:6144
	ds_read_b128 v[234:237], v149 offset:7168
	global_load_lds_dwordx4 v[144:145], off
	v_lshl_add_u64 v[144:145], s[82:83], 0, v[138:139]
	s_add_i32 m0, s63, 0xe000
	s_nop 0
	global_load_lds_dwordx4 v[144:145], off
	s_waitcnt vmcnt(24)
	s_cmp_eq_u32 s87, s62
	s_cbranch_scc1 .Lrx_br_0
	s_waitcnt vmcnt(8)
; #define PG8_STAGE(bufoff, gbase, voff) do { _Pragma("unroll") for (int _i = 0; _i < 2; ++_i) \
;         __builtin_amdgcn_global_load_lds((const unsigned*)((const char*)(gbase) + (voff)[_i]), (PG8_LAS unsigned*)(lds + (bufoff) + ldsw + _i * 8192), 16, 0, 0); } while (0)
; #define PG8_LDA(dst, b, h) do { _Pragma("unroll") for (int m = 0; m < 4; ++m) _Pragma("unroll") for (int k = 0; k < 2; ++k) dst[m][k] = *(const PG8_LAS bf16x8*)(lds + PG8_SA(b, h) + aoff + m * 2048 + k * 1024); } while (0)
; #define PG8_MMA(ai, bj, At, Bt) do { __builtin_amdgcn_s_setprio(1); _Pragma("unroll") for (int m = 0; m < 4; ++m) _Pragma("unroll") for (int n = 0; n < 2; ++n) _Pragma("unroll") for (int k = 0; k < 2; ++k) \
;         acc[ai][bj][m][n] = __builtin_amdgcn_mfma_f32_16x16x32_bf16(Bt[n][k], At[m][k], acc[ai][bj][m][n], 0, 0, 0); __builtin_amdgcn_s_setprio(0); } while (0)
; #define PG8_WAIT_V(n) asm volatile("s_waitcnt vmcnt(" #n ")" ::: "memory")
; #define PG8_WAIT_L(n) asm volatile("s_waitcnt lgkmcnt(" #n ")" ::: "memory")
; #define PG8_BAR __builtin_amdgcn_s_barrier()
; #define PG8_SCHED __builtin_amdgcn_sched_barrier(0)
; template <class Epi, class Sched, bool ALIGN_EPI = false, bool SP2 = false>
; __device__ __forceinline__ void gemm_phase(PG8_LAS unsigned char* lds, const Gemm g, const Sched& S, const Epi& E) {
;     ...
;             PG8_WAIT_V(8); PG8_WAIT_L(0); PG8_BAR; PG8_MMA(0, 0, At, B0); PG8_MMA(0, 1, At, B1); PG8_BAR; PG8_SCHED;
;             PG8_LDA(At, 0, 1); PG8_STAGE(PG8_SB(0, 0), b2, voffB); PG8_STAGE(PG8_SB(0, 1), b2 + hstep, voffB); PG8_STAGE(PG8_SA(0, 0), a2, voffA);
;             PG8_WAIT_V(8); PG8_WAIT_L(0); PG8_BAR; PG8_MMA(1, 0, At, B0); PG8_MMA(1, 1, At, B1); PG8_BAR; PG8_SCHED;
.Lrx_br_0:
	s_waitcnt lgkmcnt(0)
	s_barrier
	s_setprio 1
	s_waitcnt lgkmcnt(0)
	v_mfma_f32_16x16x32_bf16 v[124:127], v[140:143], v[184:187], v[124:127]
	v_mfma_f32_16x16x32_bf16 v[120:123], v[154:157], v[184:187], v[120:123]
	v_mfma_f32_16x16x32_bf16 v[108:111], v[140:143], v[192:195], v[108:111]
	v_mfma_f32_16x16x32_bf16 v[104:107], v[154:157], v[192:195], v[104:107]
	v_mfma_f32_16x16x32_bf16 v[92:95], v[140:143], v[222:225], v[92:95]
	v_mfma_f32_16x16x32_bf16 v[88:91], v[154:157], v[222:225], v[88:91]
	v_mfma_f32_16x16x32_bf16 v[76:79], v[140:143], v[230:233], v[76:79]
	v_mfma_f32_16x16x32_bf16 v[72:75], v[154:157], v[230:233], v[72:75]
	v_mfma_f32_16x16x32_bf16 v[124:127], v[150:153], v[188:191], v[124:127]
	v_mfma_f32_16x16x32_bf16 v[120:123], v[164:167], v[188:191], v[120:123]
	v_mfma_f32_16x16x32_bf16 v[108:111], v[150:153], v[196:199], v[108:111]
	v_mfma_f32_16x16x32_bf16 v[104:107], v[164:167], v[196:199], v[104:107]
	v_mfma_f32_16x16x32_bf16 v[92:95], v[150:153], v[226:229], v[92:95]
	v_mfma_f32_16x16x32_bf16 v[88:91], v[164:167], v[226:229], v[88:91]
	v_mfma_f32_16x16x32_bf16 v[76:79], v[150:153], v[234:237], v[76:79]
	v_mfma_f32_16x16x32_bf16 v[72:75], v[164:167], v[234:237], v[72:75]
	s_setprio 0
	s_setprio 1
	v_mfma_f32_16x16x32_bf16 v[116:119], v[168:171], v[184:187], v[116:119]
	v_mfma_f32_16x16x32_bf16 v[112:115], v[176:179], v[184:187], v[112:115]
	v_mfma_f32_16x16x32_bf16 v[100:103], v[168:171], v[192:195], v[100:103]
	v_mfma_f32_16x16x32_bf16 v[96:99], v[176:179], v[192:195], v[96:99]
	v_mfma_f32_16x16x32_bf16 v[84:87], v[168:171], v[222:225], v[84:87]
	v_mfma_f32_16x16x32_bf16 v[80:83], v[176:179], v[222:225], v[80:83]
	v_mfma_f32_16x16x32_bf16 v[68:71], v[168:171], v[230:233], v[68:71]
	v_mfma_f32_16x16x32_bf16 v[64:67], v[176:179], v[230:233], v[64:67]
	v_mfma_f32_16x16x32_bf16 v[116:119], v[172:175], v[188:191], v[116:119]
	v_mfma_f32_16x16x32_bf16 v[112:115], v[180:183], v[188:191], v[112:115]
	v_mfma_f32_16x16x32_bf16 v[100:103], v[172:175], v[196:199], v[100:103]
	v_mfma_f32_16x16x32_bf16 v[96:99], v[180:183], v[196:199], v[96:99]
	v_mfma_f32_16x16x32_bf16 v[84:87], v[172:175], v[226:229], v[84:87]
	v_mfma_f32_16x16x32_bf16 v[80:83], v[180:183], v[226:229], v[80:83]
	v_mfma_f32_16x16x32_bf16 v[68:71], v[172:175], v[234:237], v[68:71]
	v_mfma_f32_16x16x32_bf16 v[64:67], v[180:183], v[234:237], v[64:67]
	s_setprio 0
	s_barrier
	s_add_i32 s88, s88, s59
	v_lshl_add_u64 v[144:145], s[4:5], 0, v[130:131]
	s_mov_b32 m0, s88
	ds_read_b128 v[184:187], v149 offset:16384
	ds_read_b128 v[188:191], v149 offset:17408
	ds_read_b128 v[192:195], v149 offset:18432
	ds_read_b128 v[196:199], v149 offset:19456
	ds_read_b128 v[222:225], v149 offset:20480
	ds_read_b128 v[226:229], v149 offset:21504
	ds_read_b128 v[230:233], v149 offset:22528
	ds_read_b128 v[234:237], v149 offset:23552
	global_load_lds_dwordx4 v[144:145], off
	s_add_i32 m0, s88, 0x2000
	s_add_u32 s88, s4, 0x40000
	v_lshl_add_u64 v[158:159], s[4:5], 0, v[134:135]
	s_addc_u32 s89, s5, 0
	s_add_i32 s90, s90, s59
	global_load_lds_dwordx4 v[158:159], off
	v_lshl_add_u64 v[200:201], s[88:89], 0, v[130:131]
	s_mov_b32 m0, s90
	v_lshl_add_u64 v[238:239], s[52:53], 0, v[132:133]
	global_load_lds_dwordx4 v[200:201], off
	v_lshl_add_u64 v[200:201], s[88:89], 0, v[134:135]
	s_add_i32 m0, s90, 0x2000
	s_nop 0
	global_load_lds_dwordx4 v[200:201], off
	v_lshl_add_u64 v[200:201], s[52:53], 0, v[128:129]
	s_mov_b32 m0, s63
	s_nop 0
	global_load_lds_dwordx4 v[200:201], off
	s_mov_b32 m0, s74
	s_nop 0
	global_load_lds_dwordx4 v[238:239], off
	s_waitcnt vmcnt(24)
	s_cmp_eq_u32 s87, s62
	s_cbranch_scc1 .Lrx_br_1
	s_waitcnt vmcnt(8)
.Lrx_br_1:
	s_waitcnt lgkmcnt(0)
	s_barrier
	s_setprio 1
	s_waitcnt lgkmcnt(0)
	v_mfma_f32_16x16x32_bf16 v[60:63], v[140:143], v[184:187], v[60:63]
	v_mfma_f32_16x16x32_bf16 v[56:59], v[154:157], v[184:187], v[56:59]
	v_mfma_f32_16x16x32_bf16 v[44:47], v[140:143], v[192:195], v[44:47]
	v_mfma_f32_16x16x32_bf16 v[40:43], v[154:157], v[192:195], v[40:43]
	v_mfma_f32_16x16x32_bf16 v[28:31], v[140:143], v[222:225], v[28:31]
	v_mfma_f32_16x16x32_bf16 v[24:27], v[154:157], v[222:225], v[24:27]
	v_mfma_f32_16x16x32_bf16 v[12:15], v[140:143], v[230:233], v[12:15]
	v_mfma_f32_16x16x32_bf16 v[8:11], v[154:157], v[230:233], v[8:11]
	v_mfma_f32_16x16x32_bf16 v[60:63], v[150:153], v[188:191], v[60:63]
	v_mfma_f32_16x16x32_bf16 v[56:59], v[164:167], v[188:191], v[56:59]
	v_mfma_f32_16x16x32_bf16 v[44:47], v[150:153], v[196:199], v[44:47]
	v_mfma_f32_16x16x32_bf16 v[40:43], v[164:167], v[196:199], v[40:43]
	v_mfma_f32_16x16x32_bf16 v[28:31], v[150:153], v[226:229], v[28:31]
	v_mfma_f32_16x16x32_bf16 v[24:27], v[164:167], v[226:229], v[24:27]
	v_mfma_f32_16x16x32_bf16 v[12:15], v[150:153], v[234:237], v[12:15]
	v_mfma_f32_16x16x32_bf16 v[8:11], v[164:167], v[234:237], v[8:11]
	s_setprio 0
	s_setprio 1
	v_mfma_f32_16x16x32_bf16 v[52:55], v[168:171], v[184:187], v[52:55]
	v_mfma_f32_16x16x32_bf16 v[48:51], v[176:179], v[184:187], v[48:51]
	v_mfma_f32_16x16x32_bf16 v[36:39], v[168:171], v[192:195], v[36:39]
	v_mfma_f32_16x16x32_bf16 v[32:35], v[176:179], v[192:195], v[32:35]
	v_mfma_f32_16x16x32_bf16 v[20:23], v[168:171], v[222:225], v[20:23]
	v_mfma_f32_16x16x32_bf16 v[16:19], v[176:179], v[222:225], v[16:19]
	v_mfma_f32_16x16x32_bf16 v[4:7], v[168:171], v[230:233], v[4:7]
	v_mfma_f32_16x16x32_bf16 v[0:3], v[176:179], v[230:233], v[0:3]
	v_mfma_f32_16x16x32_bf16 v[52:55], v[172:175], v[188:191], v[52:55]
	v_mfma_f32_16x16x32_bf16 v[48:51], v[180:183], v[188:191], v[48:51]
	v_mfma_f32_16x16x32_bf16 v[36:39], v[172:175], v[196:199], v[36:39]
	v_mfma_f32_16x16x32_bf16 v[32:35], v[180:183], v[196:199], v[32:35]
	v_mfma_f32_16x16x32_bf16 v[20:23], v[172:175], v[226:229], v[20:23]
	v_mfma_f32_16x16x32_bf16 v[16:19], v[180:183], v[226:229], v[16:19]
	v_mfma_f32_16x16x32_bf16 v[4:7], v[172:175], v[234:237], v[4:7]
	v_mfma_f32_16x16x32_bf16 v[0:3], v[180:183], v[234:237], v[0:3]
	s_setprio 0
	s_barrier
; #define PG8_STAGE(bufoff, gbase, voff) do { _Pragma("unroll") for (int _i = 0; _i < 2; ++_i) \
;         __builtin_amdgcn_global_load_lds((const unsigned*)((const char*)(gbase) + (voff)[_i]), (PG8_LAS unsigned*)(lds + (bufoff) + ldsw + _i * 8192), 16, 0, 0); } while (0)
; #define PG8_LDA(dst, b, h) do { _Pragma("unroll") for (int m = 0; m < 4; ++m) _Pragma("unroll") for (int k = 0; k < 2; ++k) dst[m][k] = *(const PG8_LAS bf16x8*)(lds + PG8_SA(b, h) + aoff + m * 2048 + k * 1024); } while (0)
; #define PG8_LDB(dst, b, h) do { _Pragma("unroll") for (int n = 0; n < 2; ++n) _Pragma("unroll") for (int k = 0; k < 2; ++k) dst[n][k] = *(const PG8_LAS bf16x8*)(lds + PG8_SB(b, h) + boff + n * 2048 + k * 1024); } while (0)
; #define PG8_MMA(ai, bj, At, Bt) do { __builtin_amdgcn_s_setprio(1); _Pragma("unroll") for (int m = 0; m < 4; ++m) _Pragma("unroll") for (int n = 0; n < 2; ++n) _Pragma("unroll") for (int k = 0; k < 2; ++k) \
;         acc[ai][bj][m][n] = __builtin_amdgcn_mfma_f32_16x16x32_bf16(Bt[n][k], At[m][k], acc[ai][bj][m][n], 0, 0, 0); __builtin_amdgcn_s_setprio(0); } while (0)
; #define PG8_WAIT_V(n) asm volatile("s_waitcnt vmcnt(" #n ")" ::: "memory")
; #define PG8_WAIT_L(n) asm volatile("s_waitcnt lgkmcnt(" #n ")" ::: "memory")
; #define PG8_BAR __builtin_amdgcn_s_barrier()
; #define PG8_SCHED __builtin_amdgcn_sched_barrier(0)
; template <class Epi, class Sched, bool ALIGN_EPI = false, bool SP2 = false>
; __device__ __forceinline__ void gemm_phase(PG8_LAS unsigned char* lds, const Gemm g, const Sched& S, const Epi& E) {
;     ...
;             PG8_LDB(B0, 1, 0); PG8_LDB(B1, 1, 1); PG8_SCHED; PG8_LDA(At, 1, 0); PG8_STAGE(PG8_SA(0, 1), a2 + hstep, voffA);
;             PG8_WAIT_V(8); PG8_WAIT_L(0); PG8_BAR; PG8_MMA(0, 0, At, B0); PG8_MMA(0, 1, At, B1); PG8_BAR; PG8_SCHED;
	s_add_i32 s88, 0, 0x18000
	v_add_u32_e32 v160, s88, v147
	s_add_i32 s89, 0, 0x1c000
	ds_read_b128 v[140:143], v160
	ds_read_b128 v[150:153], v160 offset:1024
	ds_read_b128 v[154:157], v160 offset:2048
	ds_read_b128 v[164:167], v160 offset:3072
	v_add_u32_e32 v160, s89, v147
	ds_read_b128 v[168:171], v160
	ds_read_b128 v[172:175], v160 offset:1024
	ds_read_b128 v[176:179], v160 offset:2048
	ds_read_b128 v[180:183], v160 offset:3072
	s_add_u32 s52, s52, 0x40000
	s_addc_u32 s53, s53, 0
	s_mov_b32 m0, s75
	v_lshl_add_u64 v[240:241], s[52:53], 0, v[128:129]
	ds_read_b128 v[184:187], v149 offset:32768
	ds_read_b128 v[188:191], v149 offset:33792
	ds_read_b128 v[192:195], v149 offset:34816
	ds_read_b128 v[196:199], v149 offset:35840
	ds_read_b128 v[222:225], v149 offset:36864
	ds_read_b128 v[226:229], v149 offset:37888
	ds_read_b128 v[230:233], v149 offset:38912
	ds_read_b128 v[234:237], v149 offset:39936
	global_load_lds_dwordx4 v[240:241], off
	v_lshl_add_u64 v[240:241], s[52:53], 0, v[132:133]
	s_mov_b32 m0, s81
	s_nop 0
	global_load_lds_dwordx4 v[240:241], off
	s_waitcnt vmcnt(8)
	s_waitcnt lgkmcnt(0)
	s_barrier
	s_setprio 1
	s_waitcnt lgkmcnt(0)
	v_mfma_f32_16x16x32_bf16 v[124:127], v[140:143], v[184:187], v[124:127]
	v_mfma_f32_16x16x32_bf16 v[120:123], v[154:157], v[184:187], v[120:123]
	v_mfma_f32_16x16x32_bf16 v[108:111], v[140:143], v[192:195], v[108:111]
	v_mfma_f32_16x16x32_bf16 v[104:107], v[154:157], v[192:195], v[104:107]
	v_mfma_f32_16x16x32_bf16 v[92:95], v[140:143], v[222:225], v[92:95]
	v_mfma_f32_16x16x32_bf16 v[88:91], v[154:157], v[222:225], v[88:91]
	v_mfma_f32_16x16x32_bf16 v[76:79], v[140:143], v[230:233], v[76:79]
	v_mfma_f32_16x16x32_bf16 v[72:75], v[154:157], v[230:233], v[72:75]
	v_mfma_f32_16x16x32_bf16 v[124:127], v[150:153], v[188:191], v[124:127]
	v_mfma_f32_16x16x32_bf16 v[120:123], v[164:167], v[188:191], v[120:123]
	v_mfma_f32_16x16x32_bf16 v[108:111], v[150:153], v[196:199], v[108:111]
	v_mfma_f32_16x16x32_bf16 v[104:107], v[164:167], v[196:199], v[104:107]
	v_mfma_f32_16x16x32_bf16 v[92:95], v[150:153], v[226:229], v[92:95]
	v_mfma_f32_16x16x32_bf16 v[88:91], v[164:167], v[226:229], v[88:91]
	v_mfma_f32_16x16x32_bf16 v[76:79], v[150:153], v[234:237], v[76:79]
	v_mfma_f32_16x16x32_bf16 v[72:75], v[164:167], v[234:237], v[72:75]
	s_setprio 0
	s_setprio 1
	v_mfma_f32_16x16x32_bf16 v[116:119], v[168:171], v[184:187], v[116:119]
	v_mfma_f32_16x16x32_bf16 v[112:115], v[176:179], v[184:187], v[112:115]
	v_mfma_f32_16x16x32_bf16 v[100:103], v[168:171], v[192:195], v[100:103]
	v_mfma_f32_16x16x32_bf16 v[96:99], v[176:179], v[192:195], v[96:99]
	v_mfma_f32_16x16x32_bf16 v[84:87], v[168:171], v[222:225], v[84:87]
	v_mfma_f32_16x16x32_bf16 v[80:83], v[176:179], v[222:225], v[80:83]
	v_mfma_f32_16x16x32_bf16 v[68:71], v[168:171], v[230:233], v[68:71]
	v_mfma_f32_16x16x32_bf16 v[64:67], v[176:179], v[230:233], v[64:67]
	v_mfma_f32_16x16x32_bf16 v[116:119], v[172:175], v[188:191], v[116:119]
	v_mfma_f32_16x16x32_bf16 v[112:115], v[180:183], v[188:191], v[112:115]
	v_mfma_f32_16x16x32_bf16 v[100:103], v[172:175], v[196:199], v[100:103]
	v_mfma_f32_16x16x32_bf16 v[96:99], v[180:183], v[196:199], v[96:99]
	v_mfma_f32_16x16x32_bf16 v[84:87], v[172:175], v[226:229], v[84:87]
	v_mfma_f32_16x16x32_bf16 v[80:83], v[180:183], v[226:229], v[80:83]
	v_mfma_f32_16x16x32_bf16 v[68:71], v[172:175], v[234:237], v[68:71]
	v_mfma_f32_16x16x32_bf16 v[64:67], v[180:183], v[234:237], v[64:67]
	s_setprio 0
	s_barrier
; #define PG8_STAGE(bufoff, gbase, voff) do { _Pragma("unroll") for (int _i = 0; _i < 2; ++_i) \
;         __builtin_amdgcn_global_load_lds((const unsigned*)((const char*)(gbase) + (voff)[_i]), (PG8_LAS unsigned*)(lds + (bufoff) + ldsw + _i * 8192), 16, 0, 0); } while (0)
; #define PG8_LDA(dst, b, h) do { _Pragma("unroll") for (int m = 0; m < 4; ++m) _Pragma("unroll") for (int k = 0; k < 2; ++k) dst[m][k] = *(const PG8_LAS bf16x8*)(lds + PG8_SA(b, h) + aoff + m * 2048 + k * 1024); } while (0)
; #define PG8_MMA(ai, bj, At, Bt) do { __builtin_amdgcn_s_setprio(1); _Pragma("unroll") for (int m = 0; m < 4; ++m) _Pragma("unroll") for (int n = 0; n < 2; ++n) _Pragma("unroll") for (int k = 0; k < 2; ++k) \
;         acc[ai][bj][m][n] = __builtin_amdgcn_mfma_f32_16x16x32_bf16(Bt[n][k], At[m][k], acc[ai][bj][m][n], 0, 0, 0); __builtin_amdgcn_s_setprio(0); } while (0)
; #define PG8_WAIT_V(n) asm volatile("s_waitcnt vmcnt(" #n ")" ::: "memory")
; #define PG8_WAIT_L(n) asm volatile("s_waitcnt lgkmcnt(" #n ")" ::: "memory")
; #define PG8_BAR __builtin_amdgcn_s_barrier()
; #define PG8_SCHED __builtin_amdgcn_sched_barrier(0)
; template <class Epi, class Sched, bool ALIGN_EPI = false, bool SP2 = false>
; __device__ __forceinline__ void gemm_phase(PG8_LAS unsigned char* lds, const Gemm g, const Sched& S, const Epi& E) {
;     ...
;             PG8_LDA(At, 1, 1); PG8_STAGE(PG8_SB(1, 0), b3, voffB); PG8_STAGE(PG8_SB(1, 1), b3 + hstep, voffB); PG8_STAGE(PG8_SA(1, 0), a3, voffA);
;             PG8_WAIT_V(8); PG8_WAIT_L(0); PG8_BAR; PG8_MMA(1, 0, At, B0); PG8_MMA(1, 1, At, B1); PG8_BAR; PG8_SCHED;
	s_add_i32 s52, s88, s59
	v_lshl_add_u64 v[144:145], v[144:145], 0, s[30:31]
	s_mov_b32 m0, s52
	ds_read_b128 v[184:187], v149 offset:49152
	ds_read_b128 v[188:191], v149 offset:50176
	ds_read_b128 v[192:195], v149 offset:51200
	ds_read_b128 v[196:199], v149 offset:52224
	ds_read_b128 v[222:225], v149 offset:53248
	ds_read_b128 v[226:229], v149 offset:54272
	ds_read_b128 v[230:233], v149 offset:55296
	ds_read_b128 v[234:237], v149 offset:56320
	global_load_lds_dwordx4 v[144:145], off
	s_add_i32 m0, s52, 0x2000
	s_add_u32 s4, s4, 0x40080
	v_lshl_add_u64 v[144:145], v[158:159], 0, s[30:31]
	s_addc_u32 s5, s5, 0
	s_add_i32 s52, s89, s59
	global_load_lds_dwordx4 v[144:145], off
	v_lshl_add_u64 v[144:145], s[4:5], 0, v[130:131]
	s_mov_b32 m0, s52
	s_nop 0
	global_load_lds_dwordx4 v[144:145], off
	v_lshl_add_u64 v[144:145], s[4:5], 0, v[134:135]
	s_add_i32 m0, s52, 0x2000
	s_nop 0
	global_load_lds_dwordx4 v[144:145], off
	v_lshl_add_u64 v[144:145], v[200:201], 0, s[30:31]
	s_mov_b32 m0, s84
	s_nop 0
	global_load_lds_dwordx4 v[144:145], off
	v_lshl_add_u64 v[144:145], v[238:239], 0, s[30:31]
	s_mov_b32 m0, s85
	s_nop 0
	global_load_lds_dwordx4 v[144:145], off
	s_waitcnt vmcnt(8)
	s_waitcnt lgkmcnt(0)
	s_barrier
	s_setprio 1
	s_waitcnt lgkmcnt(0)
	v_mfma_f32_16x16x32_bf16 v[60:63], v[140:143], v[184:187], v[60:63]
	v_mfma_f32_16x16x32_bf16 v[56:59], v[154:157], v[184:187], v[56:59]
	v_mfma_f32_16x16x32_bf16 v[44:47], v[140:143], v[192:195], v[44:47]
	v_mfma_f32_16x16x32_bf16 v[40:43], v[154:157], v[192:195], v[40:43]
	v_mfma_f32_16x16x32_bf16 v[28:31], v[140:143], v[222:225], v[28:31]
	v_mfma_f32_16x16x32_bf16 v[24:27], v[154:157], v[222:225], v[24:27]
	v_mfma_f32_16x16x32_bf16 v[12:15], v[140:143], v[230:233], v[12:15]
	v_mfma_f32_16x16x32_bf16 v[8:11], v[154:157], v[230:233], v[8:11]
	v_mfma_f32_16x16x32_bf16 v[60:63], v[150:153], v[188:191], v[60:63]
	v_mfma_f32_16x16x32_bf16 v[56:59], v[164:167], v[188:191], v[56:59]
	v_mfma_f32_16x16x32_bf16 v[44:47], v[150:153], v[196:199], v[44:47]
	v_mfma_f32_16x16x32_bf16 v[40:43], v[164:167], v[196:199], v[40:43]
	v_mfma_f32_16x16x32_bf16 v[28:31], v[150:153], v[226:229], v[28:31]
	v_mfma_f32_16x16x32_bf16 v[24:27], v[164:167], v[226:229], v[24:27]
	v_mfma_f32_16x16x32_bf16 v[12:15], v[150:153], v[234:237], v[12:15]
	v_mfma_f32_16x16x32_bf16 v[8:11], v[164:167], v[234:237], v[8:11]
	s_setprio 0
	s_setprio 1
	v_mfma_f32_16x16x32_bf16 v[52:55], v[168:171], v[184:187], v[52:55]
	v_mfma_f32_16x16x32_bf16 v[48:51], v[176:179], v[184:187], v[48:51]
	v_mfma_f32_16x16x32_bf16 v[36:39], v[168:171], v[192:195], v[36:39]
	v_mfma_f32_16x16x32_bf16 v[32:35], v[176:179], v[192:195], v[32:35]
	v_mfma_f32_16x16x32_bf16 v[20:23], v[168:171], v[222:225], v[20:23]
	v_mfma_f32_16x16x32_bf16 v[16:19], v[176:179], v[222:225], v[16:19]
	v_mfma_f32_16x16x32_bf16 v[4:7], v[168:171], v[230:233], v[4:7]
	v_mfma_f32_16x16x32_bf16 v[0:3], v[176:179], v[230:233], v[0:3]
	v_mfma_f32_16x16x32_bf16 v[52:55], v[172:175], v[188:191], v[52:55]
	v_mfma_f32_16x16x32_bf16 v[48:51], v[180:183], v[188:191], v[48:51]
	v_mfma_f32_16x16x32_bf16 v[36:39], v[172:175], v[196:199], v[36:39]
	v_mfma_f32_16x16x32_bf16 v[32:35], v[180:183], v[196:199], v[32:35]
	v_mfma_f32_16x16x32_bf16 v[20:23], v[172:175], v[226:229], v[20:23]
	v_mfma_f32_16x16x32_bf16 v[16:19], v[180:183], v[226:229], v[16:19]
	v_mfma_f32_16x16x32_bf16 v[4:7], v[172:175], v[234:237], v[4:7]
	v_mfma_f32_16x16x32_bf16 v[0:3], v[180:183], v[234:237], v[0:3]
	s_setprio 0
	s_barrier
	s_add_i32 s87, s87, 2
	s_add_u32 s82, s82, 0x100
	s_addc_u32 s83, s83, 0
	s_add_u32 s29, s29, 0x100
	s_addc_u32 s43, s43, 0
	s_cmp_gt_u32 s87, 13
	s_cbranch_scc0 .LBB0_86
	s_and_b64 vcc, exec, s[12:13]
	s_cbranch_vccz .LBB0_89
	s_barrier

;     __host__ __device__ bool next(int i, Unit& u) const { if (!base.next(i >> 1, u)) return false; if (i & 1) { u.pm += 64; u.pn += 8; } return true; }
; #define PG8_STAGE(bufoff, gbase, voff) do { _Pragma("unroll") for (int _i = 0; _i < 2; ++_i) \
;         __builtin_amdgcn_global_load_lds((const unsigned*)((const char*)(gbase) + (voff)[_i]), (PG8_LAS unsigned*)(lds + (bufoff) + ldsw + _i * 8192), 16, 0, 0); } while (0)
; #define PG8_LDA(dst, b, h) do { _Pragma("unroll") for (int m = 0; m < 4; ++m) _Pragma("unroll") for (int k = 0; k < 2; ++k) dst[m][k] = *(const PG8_LAS bf16x8*)(lds + PG8_SA(b, h) + aoff + m * 2048 + k * 1024); } while (0)
; #define PG8_LDB(dst, b, h) do { _Pragma("unroll") for (int n = 0; n < 2; ++n) _Pragma("unroll") for (int k = 0; k < 2; ++k) dst[n][k] = *(const PG8_LAS bf16x8*)(lds + PG8_SB(b, h) + boff + n * 2048 + k * 1024); } while (0)
; #define PG8_SCHED __builtin_amdgcn_sched_barrier(0)
; template <class Epi, class Sched, bool ALIGN_EPI = false, bool SP2 = false>
; __device__ __forceinline__ void gemm_phase(PG8_LAS unsigned char* lds, const Gemm g, const Sched& S, const Epi& E) {
;     ...
;         const bool has_next = S.next(ui + 1, nxt);
;         const char* nA = has_next ? (const char*)g.A + (size_t)nxt.pm * tstep : cA; const char* nB = has_next ? (const char*)g.Bt + (size_t)nxt.pn * tstep : cB;
;         for (int t = 0; t < nt; t += 2) {
;             const bool last = (t == nt - 2);
;             const char* a1 = cA + (size_t)(t + 1) * kstep;
;             const char* a2 = last ? nA : cA + (size_t)(t + 2) * kstep; const char* b2 = last ? nB : cB + (size_t)(t + 2) * kstep;
;             const char* a3 = a2 + kstep; const char* b3 = b2 + kstep;
;             if (last && has_next) S.a_ready(nxt);
;             if constexpr (SP2) {
;             PG8_LDB(B0, 0, 0); PG8_LDB(B1, 0, 1); PG8_SCHED; PG8_LDA(At, 0, 0); PG8_STAGE(PG8_SA(1, 1), a1 + hstep, voffA);
;     ...
;         for (int a = 0; a < 2; ++a)
; #pragma unroll
;             for (int b = 0; b < 2; ++b)
; #pragma unroll
;                 for (int m = 0; m < 4; ++m)
; #pragma unroll
;                     for (int n = 0; n < 2; ++n) acc[a][b][m][n] = (f32x4){0.f, 0.f, 0.f, 0.f};
.LBB0_321:
	s_ashr_i32 s43, s42, 31
	s_lshl_b64 s[28:29], s[42:43], 20
	s_add_u32 s94, s66, s28
	s_addc_u32 s95, s67, s29
	s_and_b64 s[28:29], s[92:93], exec
	s_cselect_b32 s1, s95, s15
	s_cselect_b32 s28, s94, s14
	s_ashr_i32 s45, s44, 31
	s_lshl_b64 s[52:53], s[44:45], 20
	s_add_u32 s96, s24, s52
	s_addc_u32 s97, s59, s53
	s_and_b64 s[52:53], s[92:93], exec
	s_cselect_b32 s29, s97, s5
	s_cselect_b32 s43, s96, s4
	s_add_u32 s14, s14, 0x80080
	s_addc_u32 s15, s15, 0
	s_add_u32 s45, s4, 0x100
	v_mov_b32_e32 v0, 0
	s_addc_u32 s54, s5, 0
	s_mov_b32 s55, -2
	s_cmp_gt_i32 s0, 1
	s_cselect_b32 s98, -2, 0x7fffffff
	v_mov_b32_e32 v1, v0
	v_mov_b32_e32 v2, v0
	v_mov_b32_e32 v3, v0
	v_mov_b32_e32 v4, v0
	v_mov_b32_e32 v5, v0
	v_mov_b32_e32 v6, v0
	v_mov_b32_e32 v7, v0
	v_mov_b32_e32 v8, v0
	v_mov_b32_e32 v9, v0
	v_mov_b32_e32 v10, v0
	v_mov_b32_e32 v11, v0
	v_mov_b32_e32 v12, v0
	v_mov_b32_e32 v13, v0
	v_mov_b32_e32 v14, v0
	v_mov_b32_e32 v15, v0
	v_mov_b32_e32 v16, v0
	v_mov_b32_e32 v17, v0
	v_mov_b32_e32 v18, v0
	v_mov_b32_e32 v19, v0
	v_mov_b32_e32 v20, v0
	v_mov_b32_e32 v21, v0
	v_mov_b32_e32 v22, v0
	v_mov_b32_e32 v23, v0
	v_mov_b32_e32 v24, v0
	v_mov_b32_e32 v25, v0
	v_mov_b32_e32 v26, v0
	v_mov_b32_e32 v27, v0
	v_mov_b32_e32 v28, v0
	v_mov_b32_e32 v29, v0
	v_mov_b32_e32 v30, v0
	v_mov_b32_e32 v31, v0
	v_mov_b32_e32 v32, v0
	v_mov_b32_e32 v33, v0
	v_mov_b32_e32 v34, v0
	v_mov_b32_e32 v35, v0
	v_mov_b32_e32 v36, v0
	v_mov_b32_e32 v37, v0
	v_mov_b32_e32 v38, v0
	v_mov_b32_e32 v39, v0
	v_mov_b32_e32 v40, v0
	v_mov_b32_e32 v41, v0
	v_mov_b32_e32 v42, v0
	v_mov_b32_e32 v43, v0
	v_mov_b32_e32 v44, v0
	v_mov_b32_e32 v45, v0
	v_mov_b32_e32 v46, v0
	v_mov_b32_e32 v47, v0
	v_mov_b32_e32 v48, v0
	v_mov_b32_e32 v49, v0
	v_mov_b32_e32 v50, v0
	v_mov_b32_e32 v51, v0
	v_mov_b32_e32 v52, v0
	v_mov_b32_e32 v53, v0
	v_mov_b32_e32 v54, v0
	v_mov_b32_e32 v55, v0
	v_mov_b32_e32 v56, v0
	v_mov_b32_e32 v57, v0
	v_mov_b32_e32 v58, v0
	v_mov_b32_e32 v59, v0
	v_mov_b32_e32 v60, v0
	v_mov_b32_e32 v61, v0
	v_mov_b32_e32 v62, v0
	v_mov_b32_e32 v63, v0
	v_mov_b32_e32 v64, v0
	v_mov_b32_e32 v65, v0
	v_mov_b32_e32 v66, v0
	v_mov_b32_e32 v67, v0
	v_mov_b32_e32 v68, v0
	v_mov_b32_e32 v69, v0
	v_mov_b32_e32 v70, v0
	v_mov_b32_e32 v71, v0
	v_mov_b32_e32 v72, v0
	v_mov_b32_e32 v73, v0
	v_mov_b32_e32 v74, v0
	v_mov_b32_e32 v75, v0
	v_mov_b32_e32 v76, v0
	v_mov_b32_e32 v77, v0
	v_mov_b32_e32 v78, v0
	v_mov_b32_e32 v79, v0
	v_mov_b32_e32 v80, v0
	v_mov_b32_e32 v81, v0
	v_mov_b32_e32 v82, v0
	v_mov_b32_e32 v83, v0
	v_mov_b32_e32 v84, v0
	v_mov_b32_e32 v85, v0
	v_mov_b32_e32 v86, v0
	v_mov_b32_e32 v87, v0
	v_mov_b32_e32 v88, v0
	v_mov_b32_e32 v89, v0
	v_mov_b32_e32 v90, v0
	v_mov_b32_e32 v91, v0
	v_mov_b32_e32 v92, v0
	v_mov_b32_e32 v93, v0
	v_mov_b32_e32 v94, v0
	v_mov_b32_e32 v95, v0
	v_mov_b32_e32 v96, v0
	v_mov_b32_e32 v97, v0
	v_mov_b32_e32 v98, v0
	v_mov_b32_e32 v99, v0
	v_mov_b32_e32 v100, v0
	v_mov_b32_e32 v101, v0
	v_mov_b32_e32 v102, v0
	v_mov_b32_e32 v103, v0
	v_mov_b32_e32 v104, v0
	v_mov_b32_e32 v105, v0
	v_mov_b32_e32 v106, v0
	v_mov_b32_e32 v107, v0
	v_mov_b32_e32 v108, v0
	v_mov_b32_e32 v109, v0
	v_mov_b32_e32 v110, v0
	v_mov_b32_e32 v111, v0
	v_mov_b32_e32 v112, v0
	v_mov_b32_e32 v113, v0
	v_mov_b32_e32 v114, v0
	v_mov_b32_e32 v115, v0
	v_mov_b32_e32 v116, v0
	v_mov_b32_e32 v117, v0
	v_mov_b32_e32 v118, v0
	v_mov_b32_e32 v119, v0
	v_mov_b32_e32 v120, v0
	v_mov_b32_e32 v121, v0
	v_mov_b32_e32 v122, v0
	v_mov_b32_e32 v123, v0
	v_mov_b32_e32 v124, v0
	v_mov_b32_e32 v125, v0
	v_mov_b32_e32 v126, v0
	v_mov_b32_e32 v127, v0
.LBB0_322:
	s_add_u32 s4, s14, 0xfff80080
	s_addc_u32 s5, s15, -1
	s_add_i32 s56, 0, 0x10000
	s_cmp_eq_u32 s55, 28
	s_cselect_b32 s53, s1, s5
	s_cselect_b32 s52, s28, s4
	v_add_u32_e32 v158, s56, v139
	s_cselect_b32 s5, s29, s54
	s_cselect_b32 s4, s43, s45
	s_add_i32 vcc_lo, 0, 0x14000
	s_waitcnt lgkmcnt(0)
	ds_read_b128 v[154:157], v158
	ds_read_b128 v[164:167], v158 offset:1024
	ds_read_b128 v[168:171], v158 offset:2048
	ds_read_b128 v[172:175], v158 offset:3072
	v_add_u32_e32 v158, vcc_lo, v139
	ds_read_b128 v[176:179], v158
	ds_read_b128 v[180:183], v158 offset:1024
	ds_read_b128 v[184:187], v158 offset:2048
	ds_read_b128 v[188:191], v158 offset:3072
	v_lshl_add_u64 v[158:159], s[14:15], 0, v[150:151]
	s_add_i32 m0, s89, 0xc000
	ds_read_b128 v[192:195], v145
	ds_read_b128 v[196:199], v145 offset:1024
	ds_read_b128 v[222:225], v145 offset:2048
	ds_read_b128 v[226:229], v145 offset:3072
	ds_read_b128 v[230:233], v145 offset:4096
	ds_read_b128 v[234:237], v145 offset:5120
	ds_read_b128 v[238:241], v145 offset:6144
	ds_read_b128 v[242:245], v145 offset:7168
	global_load_lds_dwordx4 v[158:159], off
	v_lshl_add_u64 v[158:159], s[14:15], 0, v[152:153]
	s_add_i32 m0, s89, 0xe000
	s_nop 0
	global_load_lds_dwordx4 v[158:159], off
	s_waitcnt vmcnt(24)
	s_cmp_eq_u32 s55, s98
	s_cbranch_scc1 .Lrx_proj_0
	s_waitcnt vmcnt(8)
; #define PG8_STAGE(bufoff, gbase, voff) do { _Pragma("unroll") for (int _i = 0; _i < 2; ++_i) \
;         __builtin_amdgcn_global_load_lds((const unsigned*)((const char*)(gbase) + (voff)[_i]), (PG8_LAS unsigned*)(lds + (bufoff) + ldsw + _i * 8192), 16, 0, 0); } while (0)
; #define PG8_LDA(dst, b, h) do { _Pragma("unroll") for (int m = 0; m < 4; ++m) _Pragma("unroll") for (int k = 0; k < 2; ++k) dst[m][k] = *(const PG8_LAS bf16x8*)(lds + PG8_SA(b, h) + aoff + m * 2048 + k * 1024); } while (0)
; #define PG8_MMA(ai, bj, At, Bt) do { __builtin_amdgcn_s_setprio(1); _Pragma("unroll") for (int m = 0; m < 4; ++m) _Pragma("unroll") for (int n = 0; n < 2; ++n) _Pragma("unroll") for (int k = 0; k < 2; ++k) \
;         acc[ai][bj][m][n] = __builtin_amdgcn_mfma_f32_16x16x32_bf16(Bt[n][k], At[m][k], acc[ai][bj][m][n], 0, 0, 0); __builtin_amdgcn_s_setprio(0); } while (0)
; #define PG8_WAIT_V(n) asm volatile("s_waitcnt vmcnt(" #n ")" ::: "memory")
; #define PG8_WAIT_L(n) asm volatile("s_waitcnt lgkmcnt(" #n ")" ::: "memory")
; #define PG8_BAR __builtin_amdgcn_s_barrier()
; #define PG8_SCHED __builtin_amdgcn_sched_barrier(0)
; template <class Epi, class Sched, bool ALIGN_EPI = false, bool SP2 = false>
; __device__ __forceinline__ void gemm_phase(PG8_LAS unsigned char* lds, const Gemm g, const Sched& S, const Epi& E) {
;     ...
;             PG8_WAIT_V(8); PG8_WAIT_L(0); PG8_BAR; PG8_MMA(0, 0, At, B0); PG8_MMA(0, 1, At, B1); PG8_BAR; PG8_SCHED;
;             PG8_LDA(At, 0, 1); PG8_STAGE(PG8_SB(0, 0), b2, voffB); PG8_STAGE(PG8_SB(0, 1), b2 + hstep, voffB); PG8_STAGE(PG8_SA(0, 0), a2, voffA);
;             PG8_WAIT_V(8); PG8_WAIT_L(0); PG8_BAR; PG8_MMA(1, 0, At, B0); PG8_MMA(1, 1, At, B1); PG8_BAR; PG8_SCHED;
.Lrx_proj_0:
	s_waitcnt lgkmcnt(0)
	s_barrier
	s_setprio 1
	s_waitcnt lgkmcnt(0)
	v_mfma_f32_16x16x32_bf16 v[124:127], v[154:157], v[192:195], v[124:127]
	v_mfma_f32_16x16x32_bf16 v[120:123], v[168:171], v[192:195], v[120:123]
	v_mfma_f32_16x16x32_bf16 v[116:119], v[154:157], v[222:225], v[116:119]
	v_mfma_f32_16x16x32_bf16 v[112:115], v[168:171], v[222:225], v[112:115]
	v_mfma_f32_16x16x32_bf16 v[108:111], v[154:157], v[230:233], v[108:111]
	v_mfma_f32_16x16x32_bf16 v[104:107], v[168:171], v[230:233], v[104:107]
	v_mfma_f32_16x16x32_bf16 v[100:103], v[154:157], v[238:241], v[100:103]
	v_mfma_f32_16x16x32_bf16 v[96:99], v[168:171], v[238:241], v[96:99]
	v_mfma_f32_16x16x32_bf16 v[124:127], v[164:167], v[196:199], v[124:127]
	v_mfma_f32_16x16x32_bf16 v[120:123], v[172:175], v[196:199], v[120:123]
	v_mfma_f32_16x16x32_bf16 v[116:119], v[164:167], v[226:229], v[116:119]
	v_mfma_f32_16x16x32_bf16 v[112:115], v[172:175], v[226:229], v[112:115]
	v_mfma_f32_16x16x32_bf16 v[108:111], v[164:167], v[234:237], v[108:111]
	v_mfma_f32_16x16x32_bf16 v[104:107], v[172:175], v[234:237], v[104:107]
	v_mfma_f32_16x16x32_bf16 v[100:103], v[164:167], v[242:245], v[100:103]
	v_mfma_f32_16x16x32_bf16 v[96:99], v[172:175], v[242:245], v[96:99]
	s_setprio 0
	s_setprio 1
	v_mfma_f32_16x16x32_bf16 v[92:95], v[176:179], v[192:195], v[92:95]
	v_mfma_f32_16x16x32_bf16 v[88:91], v[184:187], v[192:195], v[88:91]
	v_mfma_f32_16x16x32_bf16 v[84:87], v[176:179], v[222:225], v[84:87]
	v_mfma_f32_16x16x32_bf16 v[80:83], v[184:187], v[222:225], v[80:83]
	v_mfma_f32_16x16x32_bf16 v[76:79], v[176:179], v[230:233], v[76:79]
	v_mfma_f32_16x16x32_bf16 v[72:75], v[184:187], v[230:233], v[72:75]
	v_mfma_f32_16x16x32_bf16 v[68:71], v[176:179], v[238:241], v[68:71]
	v_mfma_f32_16x16x32_bf16 v[64:67], v[184:187], v[238:241], v[64:67]
	v_mfma_f32_16x16x32_bf16 v[92:95], v[180:183], v[196:199], v[92:95]
	v_mfma_f32_16x16x32_bf16 v[88:91], v[188:191], v[196:199], v[88:91]
	v_mfma_f32_16x16x32_bf16 v[84:87], v[180:183], v[226:229], v[84:87]
	v_mfma_f32_16x16x32_bf16 v[80:83], v[188:191], v[226:229], v[80:83]
	v_mfma_f32_16x16x32_bf16 v[76:79], v[180:183], v[234:237], v[76:79]
	v_mfma_f32_16x16x32_bf16 v[72:75], v[188:191], v[234:237], v[72:75]
	v_mfma_f32_16x16x32_bf16 v[68:71], v[180:183], v[242:245], v[68:71]
	v_mfma_f32_16x16x32_bf16 v[64:67], v[188:191], v[242:245], v[64:67]
	s_setprio 0
	s_barrier
	s_add_i32 s56, s56, s63
	v_lshl_add_u64 v[158:159], s[4:5], 0, v[130:131]
	s_mov_b32 m0, s56
	ds_read_b128 v[192:195], v145 offset:16384
	ds_read_b128 v[196:199], v145 offset:17408
	ds_read_b128 v[222:225], v145 offset:18432
	ds_read_b128 v[226:229], v145 offset:19456
	ds_read_b128 v[230:233], v145 offset:20480
	ds_read_b128 v[234:237], v145 offset:21504
	ds_read_b128 v[238:241], v145 offset:22528
	ds_read_b128 v[242:245], v145 offset:23552
	global_load_lds_dwordx4 v[158:159], off
	s_add_i32 m0, s56, 0x2000
	s_add_u32 s56, s4, 0x80000
	v_lshl_add_u64 v[246:247], s[4:5], 0, v[134:135]
	s_addc_u32 s57, s5, 0
	s_add_i32 vcc_lo, vcc_lo, s63
	global_load_lds_dwordx4 v[246:247], off
	v_lshl_add_u64 v[248:249], s[56:57], 0, v[130:131]
	s_mov_b32 m0, vcc_lo
	v_lshl_add_u64 v[250:251], s[52:53], 0, v[132:133]
	global_load_lds_dwordx4 v[248:249], off
	v_lshl_add_u64 v[248:249], s[56:57], 0, v[134:135]
	s_add_i32 m0, vcc_lo, 0x2000
	s_nop 0
	global_load_lds_dwordx4 v[248:249], off
	v_lshl_add_u64 v[248:249], s[52:53], 0, v[128:129]
	s_mov_b32 m0, s89
	s_nop 0
	global_load_lds_dwordx4 v[248:249], off
	s_mov_b32 m0, s91
	s_nop 0
	global_load_lds_dwordx4 v[250:251], off
	s_waitcnt vmcnt(24)
	s_cmp_eq_u32 s55, s98
	s_cbranch_scc1 .Lrx_proj_1
	s_waitcnt vmcnt(8)
.Lrx_proj_1:
	s_waitcnt lgkmcnt(0)
	s_barrier
	s_setprio 1
	s_waitcnt lgkmcnt(0)
	v_mfma_f32_16x16x32_bf16 v[60:63], v[154:157], v[192:195], v[60:63]
	v_mfma_f32_16x16x32_bf16 v[56:59], v[168:171], v[192:195], v[56:59]
	v_mfma_f32_16x16x32_bf16 v[52:55], v[154:157], v[222:225], v[52:55]
	v_mfma_f32_16x16x32_bf16 v[48:51], v[168:171], v[222:225], v[48:51]
	v_mfma_f32_16x16x32_bf16 v[44:47], v[154:157], v[230:233], v[44:47]
	v_mfma_f32_16x16x32_bf16 v[40:43], v[168:171], v[230:233], v[40:43]
	v_mfma_f32_16x16x32_bf16 v[36:39], v[154:157], v[238:241], v[36:39]
	v_mfma_f32_16x16x32_bf16 v[32:35], v[168:171], v[238:241], v[32:35]
	v_mfma_f32_16x16x32_bf16 v[60:63], v[164:167], v[196:199], v[60:63]
	v_mfma_f32_16x16x32_bf16 v[56:59], v[172:175], v[196:199], v[56:59]
	v_mfma_f32_16x16x32_bf16 v[52:55], v[164:167], v[226:229], v[52:55]
	v_mfma_f32_16x16x32_bf16 v[48:51], v[172:175], v[226:229], v[48:51]
	v_mfma_f32_16x16x32_bf16 v[44:47], v[164:167], v[234:237], v[44:47]
	v_mfma_f32_16x16x32_bf16 v[40:43], v[172:175], v[234:237], v[40:43]
	v_mfma_f32_16x16x32_bf16 v[36:39], v[164:167], v[242:245], v[36:39]
	v_mfma_f32_16x16x32_bf16 v[32:35], v[172:175], v[242:245], v[32:35]
	s_setprio 0
	s_setprio 1
	v_mfma_f32_16x16x32_bf16 v[28:31], v[176:179], v[192:195], v[28:31]
	v_mfma_f32_16x16x32_bf16 v[24:27], v[184:187], v[192:195], v[24:27]
	v_mfma_f32_16x16x32_bf16 v[20:23], v[176:179], v[222:225], v[20:23]
	v_mfma_f32_16x16x32_bf16 v[16:19], v[184:187], v[222:225], v[16:19]
	v_mfma_f32_16x16x32_bf16 v[12:15], v[176:179], v[230:233], v[12:15]
	v_mfma_f32_16x16x32_bf16 v[8:11], v[184:187], v[230:233], v[8:11]
	v_mfma_f32_16x16x32_bf16 v[4:7], v[176:179], v[238:241], v[4:7]
	v_mfma_f32_16x16x32_bf16 v[0:3], v[184:187], v[238:241], v[0:3]
	v_mfma_f32_16x16x32_bf16 v[28:31], v[180:183], v[196:199], v[28:31]
	v_mfma_f32_16x16x32_bf16 v[24:27], v[188:191], v[196:199], v[24:27]
	v_mfma_f32_16x16x32_bf16 v[20:23], v[180:183], v[226:229], v[20:23]
	v_mfma_f32_16x16x32_bf16 v[16:19], v[188:191], v[226:229], v[16:19]
	v_mfma_f32_16x16x32_bf16 v[12:15], v[180:183], v[234:237], v[12:15]
	v_mfma_f32_16x16x32_bf16 v[8:11], v[188:191], v[234:237], v[8:11]
	v_mfma_f32_16x16x32_bf16 v[4:7], v[180:183], v[242:245], v[4:7]
	v_mfma_f32_16x16x32_bf16 v[0:3], v[188:191], v[242:245], v[0:3]
	s_setprio 0
	s_barrier
; #define PG8_STAGE(bufoff, gbase, voff) do { _Pragma("unroll") for (int _i = 0; _i < 2; ++_i) \
;         __builtin_amdgcn_global_load_lds((const unsigned*)((const char*)(gbase) + (voff)[_i]), (PG8_LAS unsigned*)(lds + (bufoff) + ldsw + _i * 8192), 16, 0, 0); } while (0)
; #define PG8_LDA(dst, b, h) do { _Pragma("unroll") for (int m = 0; m < 4; ++m) _Pragma("unroll") for (int k = 0; k < 2; ++k) dst[m][k] = *(const PG8_LAS bf16x8*)(lds + PG8_SA(b, h) + aoff + m * 2048 + k * 1024); } while (0)
; #define PG8_LDB(dst, b, h) do { _Pragma("unroll") for (int n = 0; n < 2; ++n) _Pragma("unroll") for (int k = 0; k < 2; ++k) dst[n][k] = *(const PG8_LAS bf16x8*)(lds + PG8_SB(b, h) + boff + n * 2048 + k * 1024); } while (0)
; #define PG8_MMA(ai, bj, At, Bt) do { __builtin_amdgcn_s_setprio(1); _Pragma("unroll") for (int m = 0; m < 4; ++m) _Pragma("unroll") for (int n = 0; n < 2; ++n) _Pragma("unroll") for (int k = 0; k < 2; ++k) \
;         acc[ai][bj][m][n] = __builtin_amdgcn_mfma_f32_16x16x32_bf16(Bt[n][k], At[m][k], acc[ai][bj][m][n], 0, 0, 0); __builtin_amdgcn_s_setprio(0); } while (0)
; #define PG8_WAIT_V(n) asm volatile("s_waitcnt vmcnt(" #n ")" ::: "memory")
; #define PG8_WAIT_L(n) asm volatile("s_waitcnt lgkmcnt(" #n ")" ::: "memory")
; #define PG8_BAR __builtin_amdgcn_s_barrier()
; #define PG8_SCHED __builtin_amdgcn_sched_barrier(0)
; template <class Epi, class Sched, bool ALIGN_EPI = false, bool SP2 = false>
; __device__ __forceinline__ void gemm_phase(PG8_LAS unsigned char* lds, const Gemm g, const Sched& S, const Epi& E) {
;     ...
;             PG8_LDB(B0, 1, 0); PG8_LDB(B1, 1, 1); PG8_SCHED; PG8_LDA(At, 1, 0); PG8_STAGE(PG8_SA(0, 1), a2 + hstep, voffA);
;             PG8_WAIT_V(8); PG8_WAIT_L(0); PG8_BAR; PG8_MMA(0, 0, At, B0); PG8_MMA(0, 1, At, B1); PG8_BAR; PG8_SCHED;
	s_add_i32 s56, 0, 0x18000
	v_add_u32_e32 v160, s56, v139
	s_add_i32 s57, 0, 0x1c000
	ds_read_b128 v[154:157], v160
	ds_read_b128 v[164:167], v160 offset:1024
	ds_read_b128 v[168:171], v160 offset:2048
	ds_read_b128 v[172:175], v160 offset:3072
	v_add_u32_e32 v160, s57, v139
	ds_read_b128 v[176:179], v160
	ds_read_b128 v[180:183], v160 offset:1024
	ds_read_b128 v[184:187], v160 offset:2048
	ds_read_b128 v[188:191], v160 offset:3072
	s_add_u32 s52, s52, 0x80000
	s_addc_u32 s53, s53, 0
	s_mov_b32 m0, s12
	v_lshl_add_u64 v[252:253], s[52:53], 0, v[128:129]
	ds_read_b128 v[192:195], v145 offset:32768
	ds_read_b128 v[196:199], v145 offset:33792
	ds_read_b128 v[222:225], v145 offset:34816
	ds_read_b128 v[226:229], v145 offset:35840
	ds_read_b128 v[230:233], v145 offset:36864
	ds_read_b128 v[234:237], v145 offset:37888
	ds_read_b128 v[238:241], v145 offset:38912
	ds_read_b128 v[242:245], v145 offset:39936
	global_load_lds_dwordx4 v[252:253], off
	v_lshl_add_u64 v[252:253], s[52:53], 0, v[132:133]
	s_mov_b32 m0, s13
	s_nop 0
	global_load_lds_dwordx4 v[252:253], off
	s_waitcnt vmcnt(8)
	s_waitcnt lgkmcnt(0)
	s_barrier
	s_setprio 1
	s_waitcnt lgkmcnt(0)
	v_mfma_f32_16x16x32_bf16 v[124:127], v[154:157], v[192:195], v[124:127]
	v_mfma_f32_16x16x32_bf16 v[120:123], v[168:171], v[192:195], v[120:123]
	v_mfma_f32_16x16x32_bf16 v[116:119], v[154:157], v[222:225], v[116:119]
	v_mfma_f32_16x16x32_bf16 v[112:115], v[168:171], v[222:225], v[112:115]
	v_mfma_f32_16x16x32_bf16 v[108:111], v[154:157], v[230:233], v[108:111]
	v_mfma_f32_16x16x32_bf16 v[104:107], v[168:171], v[230:233], v[104:107]
	v_mfma_f32_16x16x32_bf16 v[100:103], v[154:157], v[238:241], v[100:103]
	v_mfma_f32_16x16x32_bf16 v[96:99], v[168:171], v[238:241], v[96:99]
	v_mfma_f32_16x16x32_bf16 v[124:127], v[164:167], v[196:199], v[124:127]
	v_mfma_f32_16x16x32_bf16 v[120:123], v[172:175], v[196:199], v[120:123]
	v_mfma_f32_16x16x32_bf16 v[116:119], v[164:167], v[226:229], v[116:119]
	v_mfma_f32_16x16x32_bf16 v[112:115], v[172:175], v[226:229], v[112:115]
	v_mfma_f32_16x16x32_bf16 v[108:111], v[164:167], v[234:237], v[108:111]
	v_mfma_f32_16x16x32_bf16 v[104:107], v[172:175], v[234:237], v[104:107]
	v_mfma_f32_16x16x32_bf16 v[100:103], v[164:167], v[242:245], v[100:103]
	v_mfma_f32_16x16x32_bf16 v[96:99], v[172:175], v[242:245], v[96:99]
	s_setprio 0
	s_setprio 1
	v_mfma_f32_16x16x32_bf16 v[92:95], v[176:179], v[192:195], v[92:95]
	v_mfma_f32_16x16x32_bf16 v[88:91], v[184:187], v[192:195], v[88:91]
	v_mfma_f32_16x16x32_bf16 v[84:87], v[176:179], v[222:225], v[84:87]
	v_mfma_f32_16x16x32_bf16 v[80:83], v[184:187], v[222:225], v[80:83]
	v_mfma_f32_16x16x32_bf16 v[76:79], v[176:179], v[230:233], v[76:79]
	v_mfma_f32_16x16x32_bf16 v[72:75], v[184:187], v[230:233], v[72:75]
	v_mfma_f32_16x16x32_bf16 v[68:71], v[176:179], v[238:241], v[68:71]
	v_mfma_f32_16x16x32_bf16 v[64:67], v[184:187], v[238:241], v[64:67]
	v_mfma_f32_16x16x32_bf16 v[92:95], v[180:183], v[196:199], v[92:95]
	v_mfma_f32_16x16x32_bf16 v[88:91], v[188:191], v[196:199], v[88:91]
	v_mfma_f32_16x16x32_bf16 v[84:87], v[180:183], v[226:229], v[84:87]
	v_mfma_f32_16x16x32_bf16 v[80:83], v[188:191], v[226:229], v[80:83]
	v_mfma_f32_16x16x32_bf16 v[76:79], v[180:183], v[234:237], v[76:79]
	v_mfma_f32_16x16x32_bf16 v[72:75], v[188:191], v[234:237], v[72:75]
	v_mfma_f32_16x16x32_bf16 v[68:71], v[180:183], v[242:245], v[68:71]
	v_mfma_f32_16x16x32_bf16 v[64:67], v[188:191], v[242:245], v[64:67]
	s_setprio 0
	s_barrier
; #define PG8_STAGE(bufoff, gbase, voff) do { _Pragma("unroll") for (int _i = 0; _i < 2; ++_i) \
;         __builtin_amdgcn_global_load_lds((const unsigned*)((const char*)(gbase) + (voff)[_i]), (PG8_LAS unsigned*)(lds + (bufoff) + ldsw + _i * 8192), 16, 0, 0); } while (0)
; #define PG8_LDA(dst, b, h) do { _Pragma("unroll") for (int m = 0; m < 4; ++m) _Pragma("unroll") for (int k = 0; k < 2; ++k) dst[m][k] = *(const PG8_LAS bf16x8*)(lds + PG8_SA(b, h) + aoff + m * 2048 + k * 1024); } while (0)
; #define PG8_MMA(ai, bj, At, Bt) do { __builtin_amdgcn_s_setprio(1); _Pragma("unroll") for (int m = 0; m < 4; ++m) _Pragma("unroll") for (int n = 0; n < 2; ++n) _Pragma("unroll") for (int k = 0; k < 2; ++k) \
;         acc[ai][bj][m][n] = __builtin_amdgcn_mfma_f32_16x16x32_bf16(Bt[n][k], At[m][k], acc[ai][bj][m][n], 0, 0, 0); __builtin_amdgcn_s_setprio(0); } while (0)
; #define PG8_WAIT_V(n) asm volatile("s_waitcnt vmcnt(" #n ")" ::: "memory")
; #define PG8_WAIT_L(n) asm volatile("s_waitcnt lgkmcnt(" #n ")" ::: "memory")
; #define PG8_BAR __builtin_amdgcn_s_barrier()
; #define PG8_SCHED __builtin_amdgcn_sched_barrier(0)
; template <class Epi, class Sched, bool ALIGN_EPI = false, bool SP2 = false>
; __device__ __forceinline__ void gemm_phase(PG8_LAS unsigned char* lds, const Gemm g, const Sched& S, const Epi& E) {
;     ...
;             PG8_LDA(At, 1, 1); PG8_STAGE(PG8_SB(1, 0), b3, voffB); PG8_STAGE(PG8_SB(1, 1), b3 + hstep, voffB); PG8_STAGE(PG8_SA(1, 0), a3, voffA);
;             PG8_WAIT_V(8); PG8_WAIT_L(0); PG8_BAR; PG8_MMA(1, 0, At, B0); PG8_MMA(1, 1, At, B1); PG8_BAR; PG8_SCHED;
	s_add_i32 s52, s56, s63
	v_lshl_add_u64 v[158:159], v[158:159], 0, s[30:31]
	s_mov_b32 m0, s52
	ds_read_b128 v[192:195], v145 offset:49152
	ds_read_b128 v[196:199], v145 offset:50176
	ds_read_b128 v[222:225], v145 offset:51200
	ds_read_b128 v[226:229], v145 offset:52224
	ds_read_b128 v[230:233], v145 offset:53248
	ds_read_b128 v[234:237], v145 offset:54272
	ds_read_b128 v[238:241], v145 offset:55296
	ds_read_b128 v[242:245], v145 offset:56320
	global_load_lds_dwordx4 v[158:159], off
	s_add_i32 m0, s52, 0x2000
	s_add_u32 s4, s4, 0x80080
	v_lshl_add_u64 v[158:159], v[246:247], 0, s[30:31]
	s_addc_u32 s5, s5, 0
	s_add_i32 s52, s57, s63
	global_load_lds_dwordx4 v[158:159], off
	v_lshl_add_u64 v[158:159], s[4:5], 0, v[130:131]
	s_mov_b32 m0, s52
	s_nop 0
	global_load_lds_dwordx4 v[158:159], off
	v_lshl_add_u64 v[158:159], s[4:5], 0, v[134:135]
	s_add_i32 m0, s52, 0x2000
	s_nop 0
	global_load_lds_dwordx4 v[158:159], off
	v_lshl_add_u64 v[158:159], v[248:249], 0, s[30:31]
	s_mov_b32 m0, s78
	s_nop 0
	global_load_lds_dwordx4 v[158:159], off
	v_lshl_add_u64 v[158:159], v[250:251], 0, s[30:31]
	s_mov_b32 m0, s79
	s_nop 0
	global_load_lds_dwordx4 v[158:159], off
	s_waitcnt vmcnt(8)
	s_waitcnt lgkmcnt(0)
	s_barrier
	s_setprio 1
	s_waitcnt lgkmcnt(0)
	v_mfma_f32_16x16x32_bf16 v[60:63], v[154:157], v[192:195], v[60:63]
	v_mfma_f32_16x16x32_bf16 v[56:59], v[168:171], v[192:195], v[56:59]
	v_mfma_f32_16x16x32_bf16 v[52:55], v[154:157], v[222:225], v[52:55]
	v_mfma_f32_16x16x32_bf16 v[48:51], v[168:171], v[222:225], v[48:51]
	v_mfma_f32_16x16x32_bf16 v[44:47], v[154:157], v[230:233], v[44:47]
	v_mfma_f32_16x16x32_bf16 v[40:43], v[168:171], v[230:233], v[40:43]
	v_mfma_f32_16x16x32_bf16 v[36:39], v[154:157], v[238:241], v[36:39]
	v_mfma_f32_16x16x32_bf16 v[32:35], v[168:171], v[238:241], v[32:35]
	v_mfma_f32_16x16x32_bf16 v[60:63], v[164:167], v[196:199], v[60:63]
	v_mfma_f32_16x16x32_bf16 v[56:59], v[172:175], v[196:199], v[56:59]
	v_mfma_f32_16x16x32_bf16 v[52:55], v[164:167], v[226:229], v[52:55]
	v_mfma_f32_16x16x32_bf16 v[48:51], v[172:175], v[226:229], v[48:51]
	v_mfma_f32_16x16x32_bf16 v[44:47], v[164:167], v[234:237], v[44:47]
	v_mfma_f32_16x16x32_bf16 v[40:43], v[172:175], v[234:237], v[40:43]
	v_mfma_f32_16x16x32_bf16 v[36:39], v[164:167], v[242:245], v[36:39]
	v_mfma_f32_16x16x32_bf16 v[32:35], v[172:175], v[242:245], v[32:35]
	s_setprio 0
	s_setprio 1
	v_mfma_f32_16x16x32_bf16 v[28:31], v[176:179], v[192:195], v[28:31]
	v_mfma_f32_16x16x32_bf16 v[24:27], v[184:187], v[192:195], v[24:27]
	v_mfma_f32_16x16x32_bf16 v[20:23], v[176:179], v[222:225], v[20:23]
	v_mfma_f32_16x16x32_bf16 v[16:19], v[184:187], v[222:225], v[16:19]
	v_mfma_f32_16x16x32_bf16 v[12:15], v[176:179], v[230:233], v[12:15]
	v_mfma_f32_16x16x32_bf16 v[8:11], v[184:187], v[230:233], v[8:11]
	v_mfma_f32_16x16x32_bf16 v[4:7], v[176:179], v[238:241], v[4:7]
	v_mfma_f32_16x16x32_bf16 v[0:3], v[184:187], v[238:241], v[0:3]
	v_mfma_f32_16x16x32_bf16 v[28:31], v[180:183], v[196:199], v[28:31]
	v_mfma_f32_16x16x32_bf16 v[24:27], v[188:191], v[196:199], v[24:27]
	v_mfma_f32_16x16x32_bf16 v[20:23], v[180:183], v[226:229], v[20:23]
	v_mfma_f32_16x16x32_bf16 v[16:19], v[188:191], v[226:229], v[16:19]
	v_mfma_f32_16x16x32_bf16 v[12:15], v[180:183], v[234:237], v[12:15]
	v_mfma_f32_16x16x32_bf16 v[8:11], v[188:191], v[234:237], v[8:11]
	v_mfma_f32_16x16x32_bf16 v[4:7], v[180:183], v[242:245], v[4:7]
	v_mfma_f32_16x16x32_bf16 v[0:3], v[188:191], v[242:245], v[0:3]
	s_setprio 0
	s_barrier
	s_add_i32 s55, s55, 2
	s_add_u32 s14, s14, 0x100
	s_addc_u32 s15, s15, 0
	s_add_u32 s45, s45, 0x100
	s_addc_u32 s54, s54, 0
	s_cmp_gt_u32 s55, 29
	s_cbranch_scc0 .LBB0_322
	s_and_b64 vcc, exec, s[82:83]
	s_cbranch_vccz .LBB0_325
	s_barrier

;     __host__ __device__ bool next(int i, Unit& u) const { if (!base.next(i >> 1, u)) return false; if (i & 1) { u.pm += 64; u.pn += 8; } return true; }
; #define PG8_STAGE(bufoff, gbase, voff) do { _Pragma("unroll") for (int _i = 0; _i < 2; ++_i) \
;         __builtin_amdgcn_global_load_lds((const unsigned*)((const char*)(gbase) + (voff)[_i]), (PG8_LAS unsigned*)(lds + (bufoff) + ldsw + _i * 8192), 16, 0, 0); } while (0)
; #define PG8_LDA(dst, b, h) do { _Pragma("unroll") for (int m = 0; m < 4; ++m) _Pragma("unroll") for (int k = 0; k < 2; ++k) dst[m][k] = *(const PG8_LAS bf16x8*)(lds + PG8_SA(b, h) + aoff + m * 2048 + k * 1024); } while (0)
; #define PG8_LDB(dst, b, h) do { _Pragma("unroll") for (int n = 0; n < 2; ++n) _Pragma("unroll") for (int k = 0; k < 2; ++k) dst[n][k] = *(const PG8_LAS bf16x8*)(lds + PG8_SB(b, h) + boff + n * 2048 + k * 1024); } while (0)
; #define PG8_SCHED __builtin_amdgcn_sched_barrier(0)
; template <class Epi, class Sched, bool ALIGN_EPI = false, bool SP2 = false>
; __device__ __forceinline__ void gemm_phase(PG8_LAS unsigned char* lds, const Gemm g, const Sched& S, const Epi& E) {
;     ...
;         const bool has_next = S.next(ui + 1, nxt);
;         const char* nA = has_next ? (const char*)g.A + (size_t)nxt.pm * tstep : cA; const char* nB = has_next ? (const char*)g.Bt + (size_t)nxt.pn * tstep : cB;
;         for (int t = 0; t < nt; t += 2) {
;             const bool last = (t == nt - 2);
;             const char* a1 = cA + (size_t)(t + 1) * kstep;
;             const char* a2 = last ? nA : cA + (size_t)(t + 2) * kstep; const char* b2 = last ? nB : cB + (size_t)(t + 2) * kstep;
;             const char* a3 = a2 + kstep; const char* b3 = b2 + kstep;
;             if (last && has_next) S.a_ready(nxt);
;             if constexpr (SP2) {
;             PG8_LDB(B0, 0, 0); PG8_LDB(B1, 0, 1); PG8_SCHED; PG8_LDA(At, 0, 0); PG8_STAGE(PG8_SA(1, 1), a1 + hstep, voffA);
;     ...
;         for (int a = 0; a < 2; ++a)
; #pragma unroll
;             for (int b = 0; b < 2; ++b)
; #pragma unroll
;                 for (int m = 0; m < 4; ++m)
; #pragma unroll
;                     for (int n = 0; n < 2; ++n) acc[a][b][m][n] = (f32x4){0.f, 0.f, 0.f, 0.f};
.LBB0_848:
	s_ashr_i32 s11, s10, 31
	s_lshl_b64 s[42:43], s[10:11], 20
	s_add_u32 s42, s66, s42
	s_addc_u32 s43, s67, s43
	s_and_b64 s[44:45], s[14:15], exec
	s_cselect_b32 s11, s43, s53
	s_cselect_b32 s63, s42, s52
	s_ashr_i32 s13, s12, 31
	s_lshl_b64 s[44:45], s[12:13], 20
	s_add_u32 s44, s0, s44
	s_addc_u32 s45, s1, s45
	s_and_b64 s[70:71], s[14:15], exec
	s_cselect_b32 s13, s45, s5
	s_cselect_b32 s72, s44, s4
	s_add_u32 s70, s52, 0x80080
	s_addc_u32 s71, s53, 0
	s_add_u32 s73, s4, 0x100
	v_mov_b32_e32 v0, 0
	s_addc_u32 s74, s5, 0
	s_mov_b32 s75, -2
	s_cmp_gt_i32 s28, 1
	s_cselect_b32 s98, -2, 0x7fffffff
	v_mov_b32_e32 v1, v0
	v_mov_b32_e32 v2, v0
	v_mov_b32_e32 v3, v0
	v_mov_b32_e32 v8, v0
	v_mov_b32_e32 v9, v0
	v_mov_b32_e32 v10, v0
	v_mov_b32_e32 v11, v0
	v_mov_b32_e32 v16, v0
	v_mov_b32_e32 v17, v0
	v_mov_b32_e32 v18, v0
	v_mov_b32_e32 v19, v0
	v_mov_b32_e32 v24, v0
	v_mov_b32_e32 v25, v0
	v_mov_b32_e32 v26, v0
	v_mov_b32_e32 v27, v0
	v_mov_b32_e32 v32, v0
	v_mov_b32_e32 v33, v0
	v_mov_b32_e32 v34, v0
	v_mov_b32_e32 v35, v0
	v_mov_b32_e32 v40, v0
	v_mov_b32_e32 v41, v0
	v_mov_b32_e32 v42, v0
	v_mov_b32_e32 v43, v0
	v_mov_b32_e32 v48, v0
	v_mov_b32_e32 v49, v0
	v_mov_b32_e32 v50, v0
	v_mov_b32_e32 v51, v0
	v_mov_b32_e32 v56, v0
	v_mov_b32_e32 v57, v0
	v_mov_b32_e32 v58, v0
	v_mov_b32_e32 v59, v0
	v_mov_b32_e32 v4, v0
	v_mov_b32_e32 v5, v0
	v_mov_b32_e32 v6, v0
	v_mov_b32_e32 v7, v0
	v_mov_b32_e32 v12, v0
	v_mov_b32_e32 v13, v0
	v_mov_b32_e32 v14, v0
	v_mov_b32_e32 v15, v0
	v_mov_b32_e32 v20, v0
	v_mov_b32_e32 v21, v0
	v_mov_b32_e32 v22, v0
	v_mov_b32_e32 v23, v0
	v_mov_b32_e32 v28, v0
	v_mov_b32_e32 v29, v0
	v_mov_b32_e32 v30, v0
	v_mov_b32_e32 v31, v0
	v_mov_b32_e32 v36, v0
	v_mov_b32_e32 v37, v0
	v_mov_b32_e32 v38, v0
	v_mov_b32_e32 v39, v0
	v_mov_b32_e32 v44, v0
	v_mov_b32_e32 v45, v0
	v_mov_b32_e32 v46, v0
	v_mov_b32_e32 v47, v0
	v_mov_b32_e32 v52, v0
	v_mov_b32_e32 v53, v0
	v_mov_b32_e32 v54, v0
	v_mov_b32_e32 v55, v0
	v_mov_b32_e32 v60, v0
	v_mov_b32_e32 v61, v0
	v_mov_b32_e32 v62, v0
	v_mov_b32_e32 v63, v0
	v_mov_b32_e32 v64, v0
	v_mov_b32_e32 v65, v0
	v_mov_b32_e32 v66, v0
	v_mov_b32_e32 v67, v0
	v_mov_b32_e32 v72, v0
	v_mov_b32_e32 v73, v0
	v_mov_b32_e32 v74, v0
	v_mov_b32_e32 v75, v0
	v_mov_b32_e32 v80, v0
	v_mov_b32_e32 v81, v0
	v_mov_b32_e32 v82, v0
	v_mov_b32_e32 v83, v0
	v_mov_b32_e32 v88, v0
	v_mov_b32_e32 v89, v0
	v_mov_b32_e32 v90, v0
	v_mov_b32_e32 v91, v0
	v_mov_b32_e32 v96, v0
	v_mov_b32_e32 v97, v0
	v_mov_b32_e32 v98, v0
	v_mov_b32_e32 v99, v0
	v_mov_b32_e32 v104, v0
	v_mov_b32_e32 v105, v0
	v_mov_b32_e32 v106, v0
	v_mov_b32_e32 v107, v0
	v_mov_b32_e32 v112, v0
	v_mov_b32_e32 v113, v0
	v_mov_b32_e32 v114, v0
	v_mov_b32_e32 v115, v0
	v_mov_b32_e32 v120, v0
	v_mov_b32_e32 v121, v0
	v_mov_b32_e32 v122, v0
	v_mov_b32_e32 v123, v0
	v_mov_b32_e32 v68, v0
	v_mov_b32_e32 v69, v0
	v_mov_b32_e32 v70, v0
	v_mov_b32_e32 v71, v0
	v_mov_b32_e32 v76, v0
	v_mov_b32_e32 v77, v0
	v_mov_b32_e32 v78, v0
	v_mov_b32_e32 v79, v0
	v_mov_b32_e32 v84, v0
	v_mov_b32_e32 v85, v0
	v_mov_b32_e32 v86, v0
	v_mov_b32_e32 v87, v0
	v_mov_b32_e32 v92, v0
	v_mov_b32_e32 v93, v0
	v_mov_b32_e32 v94, v0
	v_mov_b32_e32 v95, v0
	v_mov_b32_e32 v100, v0
	v_mov_b32_e32 v101, v0
	v_mov_b32_e32 v102, v0
	v_mov_b32_e32 v103, v0
	v_mov_b32_e32 v108, v0
	v_mov_b32_e32 v109, v0
	v_mov_b32_e32 v110, v0
	v_mov_b32_e32 v111, v0
	v_mov_b32_e32 v116, v0
	v_mov_b32_e32 v117, v0
	v_mov_b32_e32 v118, v0
	v_mov_b32_e32 v119, v0
	v_mov_b32_e32 v124, v0
	v_mov_b32_e32 v125, v0
	v_mov_b32_e32 v126, v0
	v_mov_b32_e32 v127, v0
.LBB0_849:
	s_add_u32 s4, s70, 0xfff80080
	s_addc_u32 s5, s71, -1
	s_add_i32 s76, 0, 0x10000
	s_cmp_eq_u32 s75, 28
	s_cselect_b32 s53, s11, s5
	s_cselect_b32 s52, s63, s4
	v_add_u32_e32 v138, s76, v141
	s_cselect_b32 s5, s13, s74
	s_cselect_b32 s4, s72, s73
	s_add_i32 s78, 0, 0x14000
	ds_read_b128 v[144:147], v138
	ds_read_b128 v[148:151], v138 offset:1024
	ds_read_b128 v[152:155], v138 offset:2048
	ds_read_b128 v[156:159], v138 offset:3072
	v_add_u32_e32 v138, s78, v141
	ds_read_b128 v[164:167], v138
	ds_read_b128 v[168:171], v138 offset:1024
	ds_read_b128 v[172:175], v138 offset:2048
	ds_read_b128 v[176:179], v138 offset:3072
	v_lshl_add_u64 v[138:139], s[70:71], 0, v[134:135]
	s_add_i32 m0, s51, 0xc000
	ds_read_b128 v[180:183], v143
	ds_read_b128 v[184:187], v143 offset:1024
	ds_read_b128 v[188:191], v143 offset:2048
	ds_read_b128 v[192:195], v143 offset:3072
	ds_read_b128 v[196:199], v143 offset:4096
	ds_read_b128 v[222:225], v143 offset:5120
	ds_read_b128 v[226:229], v143 offset:6144
	ds_read_b128 v[230:233], v143 offset:7168
	global_load_lds_dwordx4 v[138:139], off
	v_lshl_add_u64 v[138:139], s[70:71], 0, v[136:137]
	s_add_i32 m0, s51, 0xe000
	s_nop 0
	global_load_lds_dwordx4 v[138:139], off
	s_waitcnt vmcnt(16)
	s_cmp_eq_u32 s75, s98
	s_cbranch_scc1 .Lrx_gu_0
	s_waitcnt vmcnt(8)
; #define PG8_STAGE(bufoff, gbase, voff) do { _Pragma("unroll") for (int _i = 0; _i < 2; ++_i) \
;         __builtin_amdgcn_global_load_lds((const unsigned*)((const char*)(gbase) + (voff)[_i]), (PG8_LAS unsigned*)(lds + (bufoff) + ldsw + _i * 8192), 16, 0, 0); } while (0)
; #define PG8_LDA(dst, b, h) do { _Pragma("unroll") for (int m = 0; m < 4; ++m) _Pragma("unroll") for (int k = 0; k < 2; ++k) dst[m][k] = *(const PG8_LAS bf16x8*)(lds + PG8_SA(b, h) + aoff + m * 2048 + k * 1024); } while (0)
; #define PG8_MMA(ai, bj, At, Bt) do { __builtin_amdgcn_s_setprio(1); _Pragma("unroll") for (int m = 0; m < 4; ++m) _Pragma("unroll") for (int n = 0; n < 2; ++n) _Pragma("unroll") for (int k = 0; k < 2; ++k) \
;         acc[ai][bj][m][n] = __builtin_amdgcn_mfma_f32_16x16x32_bf16(Bt[n][k], At[m][k], acc[ai][bj][m][n], 0, 0, 0); __builtin_amdgcn_s_setprio(0); } while (0)
; #define PG8_WAIT_V(n) asm volatile("s_waitcnt vmcnt(" #n ")" ::: "memory")
; #define PG8_WAIT_L(n) asm volatile("s_waitcnt lgkmcnt(" #n ")" ::: "memory")
; #define PG8_BAR __builtin_amdgcn_s_barrier()
; #define PG8_SCHED __builtin_amdgcn_sched_barrier(0)
; template <class Epi, class Sched, bool ALIGN_EPI = false, bool SP2 = false>
; __device__ __forceinline__ void gemm_phase(PG8_LAS unsigned char* lds, const Gemm g, const Sched& S, const Epi& E) {
;     ...
;             PG8_WAIT_V(8); PG8_WAIT_L(0); PG8_BAR; PG8_MMA(0, 0, At, B0); PG8_MMA(0, 1, At, B1); PG8_BAR; PG8_SCHED;
;             PG8_LDA(At, 0, 1); PG8_STAGE(PG8_SB(0, 0), b2, voffB); PG8_STAGE(PG8_SB(0, 1), b2 + hstep, voffB); PG8_STAGE(PG8_SA(0, 0), a2, voffA);
;             PG8_WAIT_V(8); PG8_WAIT_L(0); PG8_BAR; PG8_MMA(1, 0, At, B0); PG8_MMA(1, 1, At, B1); PG8_BAR; PG8_SCHED;
.Lrx_gu_0:
	s_waitcnt lgkmcnt(0)
	s_barrier
	s_setprio 1
	s_waitcnt lgkmcnt(0)
	v_mfma_f32_16x16x32_bf16 v[124:127], v[144:147], v[180:183], v[124:127]
	v_mfma_f32_16x16x32_bf16 v[116:119], v[152:155], v[180:183], v[116:119]
	v_mfma_f32_16x16x32_bf16 v[108:111], v[144:147], v[188:191], v[108:111]
	v_mfma_f32_16x16x32_bf16 v[100:103], v[152:155], v[188:191], v[100:103]
	v_mfma_f32_16x16x32_bf16 v[92:95], v[144:147], v[196:199], v[92:95]
	v_mfma_f32_16x16x32_bf16 v[84:87], v[152:155], v[196:199], v[84:87]
	v_mfma_f32_16x16x32_bf16 v[76:79], v[144:147], v[226:229], v[76:79]
	v_mfma_f32_16x16x32_bf16 v[68:71], v[152:155], v[226:229], v[68:71]
	v_mfma_f32_16x16x32_bf16 v[124:127], v[148:151], v[184:187], v[124:127]
	v_mfma_f32_16x16x32_bf16 v[116:119], v[156:159], v[184:187], v[116:119]
	v_mfma_f32_16x16x32_bf16 v[108:111], v[148:151], v[192:195], v[108:111]
	v_mfma_f32_16x16x32_bf16 v[100:103], v[156:159], v[192:195], v[100:103]
	v_mfma_f32_16x16x32_bf16 v[92:95], v[148:151], v[222:225], v[92:95]
	v_mfma_f32_16x16x32_bf16 v[84:87], v[156:159], v[222:225], v[84:87]
	v_mfma_f32_16x16x32_bf16 v[76:79], v[148:151], v[230:233], v[76:79]
	v_mfma_f32_16x16x32_bf16 v[68:71], v[156:159], v[230:233], v[68:71]
	s_setprio 0
	s_setprio 1
	v_mfma_f32_16x16x32_bf16 v[120:123], v[164:167], v[180:183], v[120:123]
	v_mfma_f32_16x16x32_bf16 v[112:115], v[172:175], v[180:183], v[112:115]
	v_mfma_f32_16x16x32_bf16 v[104:107], v[164:167], v[188:191], v[104:107]
	v_mfma_f32_16x16x32_bf16 v[96:99], v[172:175], v[188:191], v[96:99]
	v_mfma_f32_16x16x32_bf16 v[88:91], v[164:167], v[196:199], v[88:91]
	v_mfma_f32_16x16x32_bf16 v[80:83], v[172:175], v[196:199], v[80:83]
	v_mfma_f32_16x16x32_bf16 v[72:75], v[164:167], v[226:229], v[72:75]
	v_mfma_f32_16x16x32_bf16 v[64:67], v[172:175], v[226:229], v[64:67]
	v_mfma_f32_16x16x32_bf16 v[120:123], v[168:171], v[184:187], v[120:123]
	v_mfma_f32_16x16x32_bf16 v[112:115], v[176:179], v[184:187], v[112:115]
	v_mfma_f32_16x16x32_bf16 v[104:107], v[168:171], v[192:195], v[104:107]
	v_mfma_f32_16x16x32_bf16 v[96:99], v[176:179], v[192:195], v[96:99]
	v_mfma_f32_16x16x32_bf16 v[88:91], v[168:171], v[222:225], v[88:91]
	v_mfma_f32_16x16x32_bf16 v[80:83], v[176:179], v[222:225], v[80:83]
	v_mfma_f32_16x16x32_bf16 v[72:75], v[168:171], v[230:233], v[72:75]
	v_mfma_f32_16x16x32_bf16 v[64:67], v[176:179], v[230:233], v[64:67]
	s_setprio 0
	s_barrier
	s_add_i32 s76, s76, s24
	v_lshl_add_u64 v[138:139], s[4:5], 0, v[160:161]
	s_mov_b32 m0, s76
	ds_read_b128 v[180:183], v143 offset:16384
	ds_read_b128 v[184:187], v143 offset:17408
	ds_read_b128 v[188:191], v143 offset:18432
	ds_read_b128 v[192:195], v143 offset:19456
	ds_read_b128 v[196:199], v143 offset:20480
	ds_read_b128 v[222:225], v143 offset:21504
	ds_read_b128 v[226:229], v143 offset:22528
	ds_read_b128 v[230:233], v143 offset:23552
	global_load_lds_dwordx4 v[138:139], off
	s_add_i32 m0, s76, 0x2000
	s_add_u32 s76, s4, 0x80000
	v_lshl_add_u64 v[200:201], s[4:5], 0, v[128:129]
	s_addc_u32 s77, s5, 0
	s_add_i32 s78, s78, s24
	global_load_lds_dwordx4 v[200:201], off
	v_lshl_add_u64 v[234:235], s[76:77], 0, v[160:161]
	s_mov_b32 m0, s78
	v_lshl_add_u64 v[236:237], s[52:53], 0, v[130:131]
	global_load_lds_dwordx4 v[234:235], off
	v_lshl_add_u64 v[234:235], s[76:77], 0, v[128:129]
	s_add_i32 m0, s78, 0x2000
	s_nop 0
	global_load_lds_dwordx4 v[234:235], off
	v_lshl_add_u64 v[234:235], s[52:53], 0, v[132:133]
	s_mov_b32 m0, s51
	s_nop 0
	global_load_lds_dwordx4 v[234:235], off
	s_mov_b32 m0, s55
	s_nop 0
	global_load_lds_dwordx4 v[236:237], off
	s_waitcnt vmcnt(16)
	s_cmp_eq_u32 s75, s98
	s_cbranch_scc1 .Lrx_gu_1
	s_waitcnt vmcnt(8)
.Lrx_gu_1:
	s_waitcnt lgkmcnt(0)
	s_barrier
	s_setprio 1
	s_waitcnt lgkmcnt(0)
	v_mfma_f32_16x16x32_bf16 v[60:63], v[144:147], v[180:183], v[60:63]
	v_mfma_f32_16x16x32_bf16 v[52:55], v[152:155], v[180:183], v[52:55]
	v_mfma_f32_16x16x32_bf16 v[44:47], v[144:147], v[188:191], v[44:47]
	v_mfma_f32_16x16x32_bf16 v[36:39], v[152:155], v[188:191], v[36:39]
	v_mfma_f32_16x16x32_bf16 v[28:31], v[144:147], v[196:199], v[28:31]
	v_mfma_f32_16x16x32_bf16 v[20:23], v[152:155], v[196:199], v[20:23]
	v_mfma_f32_16x16x32_bf16 v[12:15], v[144:147], v[226:229], v[12:15]
	v_mfma_f32_16x16x32_bf16 v[4:7], v[152:155], v[226:229], v[4:7]
	v_mfma_f32_16x16x32_bf16 v[60:63], v[148:151], v[184:187], v[60:63]
	v_mfma_f32_16x16x32_bf16 v[52:55], v[156:159], v[184:187], v[52:55]
	v_mfma_f32_16x16x32_bf16 v[44:47], v[148:151], v[192:195], v[44:47]
	v_mfma_f32_16x16x32_bf16 v[36:39], v[156:159], v[192:195], v[36:39]
	v_mfma_f32_16x16x32_bf16 v[28:31], v[148:151], v[222:225], v[28:31]
	v_mfma_f32_16x16x32_bf16 v[20:23], v[156:159], v[222:225], v[20:23]
	v_mfma_f32_16x16x32_bf16 v[12:15], v[148:151], v[230:233], v[12:15]
	v_mfma_f32_16x16x32_bf16 v[4:7], v[156:159], v[230:233], v[4:7]
	s_setprio 0
	s_setprio 1
	v_mfma_f32_16x16x32_bf16 v[56:59], v[164:167], v[180:183], v[56:59]
	v_mfma_f32_16x16x32_bf16 v[48:51], v[172:175], v[180:183], v[48:51]
	v_mfma_f32_16x16x32_bf16 v[40:43], v[164:167], v[188:191], v[40:43]
	v_mfma_f32_16x16x32_bf16 v[32:35], v[172:175], v[188:191], v[32:35]
	v_mfma_f32_16x16x32_bf16 v[24:27], v[164:167], v[196:199], v[24:27]
	v_mfma_f32_16x16x32_bf16 v[16:19], v[172:175], v[196:199], v[16:19]
	v_mfma_f32_16x16x32_bf16 v[8:11], v[164:167], v[226:229], v[8:11]
	v_mfma_f32_16x16x32_bf16 v[0:3], v[172:175], v[226:229], v[0:3]
	v_mfma_f32_16x16x32_bf16 v[56:59], v[168:171], v[184:187], v[56:59]
	v_mfma_f32_16x16x32_bf16 v[48:51], v[176:179], v[184:187], v[48:51]
	v_mfma_f32_16x16x32_bf16 v[40:43], v[168:171], v[192:195], v[40:43]
	v_mfma_f32_16x16x32_bf16 v[32:35], v[176:179], v[192:195], v[32:35]
	v_mfma_f32_16x16x32_bf16 v[24:27], v[168:171], v[222:225], v[24:27]
	v_mfma_f32_16x16x32_bf16 v[16:19], v[176:179], v[222:225], v[16:19]
	v_mfma_f32_16x16x32_bf16 v[8:11], v[168:171], v[230:233], v[8:11]
	v_mfma_f32_16x16x32_bf16 v[0:3], v[176:179], v[230:233], v[0:3]
	s_setprio 0
	s_barrier
; #define PG8_STAGE(bufoff, gbase, voff) do { _Pragma("unroll") for (int _i = 0; _i < 2; ++_i) \
;         __builtin_amdgcn_global_load_lds((const unsigned*)((const char*)(gbase) + (voff)[_i]), (PG8_LAS unsigned*)(lds + (bufoff) + ldsw + _i * 8192), 16, 0, 0); } while (0)
; #define PG8_LDA(dst, b, h) do { _Pragma("unroll") for (int m = 0; m < 4; ++m) _Pragma("unroll") for (int k = 0; k < 2; ++k) dst[m][k] = *(const PG8_LAS bf16x8*)(lds + PG8_SA(b, h) + aoff + m * 2048 + k * 1024); } while (0)
; #define PG8_LDB(dst, b, h) do { _Pragma("unroll") for (int n = 0; n < 2; ++n) _Pragma("unroll") for (int k = 0; k < 2; ++k) dst[n][k] = *(const PG8_LAS bf16x8*)(lds + PG8_SB(b, h) + boff + n * 2048 + k * 1024); } while (0)
; #define PG8_MMA(ai, bj, At, Bt) do { __builtin_amdgcn_s_setprio(1); _Pragma("unroll") for (int m = 0; m < 4; ++m) _Pragma("unroll") for (int n = 0; n < 2; ++n) _Pragma("unroll") for (int k = 0; k < 2; ++k) \
;         acc[ai][bj][m][n] = __builtin_amdgcn_mfma_f32_16x16x32_bf16(Bt[n][k], At[m][k], acc[ai][bj][m][n], 0, 0, 0); __builtin_amdgcn_s_setprio(0); } while (0)
; #define PG8_WAIT_V(n) asm volatile("s_waitcnt vmcnt(" #n ")" ::: "memory")
; #define PG8_WAIT_L(n) asm volatile("s_waitcnt lgkmcnt(" #n ")" ::: "memory")
; #define PG8_BAR __builtin_amdgcn_s_barrier()
; #define PG8_SCHED __builtin_amdgcn_sched_barrier(0)
; template <class Epi, class Sched, bool ALIGN_EPI = false, bool SP2 = false>
; __device__ __forceinline__ void gemm_phase(PG8_LAS unsigned char* lds, const Gemm g, const Sched& S, const Epi& E) {
;     ...
;             PG8_LDB(B0, 1, 0); PG8_LDB(B1, 1, 1); PG8_SCHED; PG8_LDA(At, 1, 0); PG8_STAGE(PG8_SA(0, 1), a2 + hstep, voffA);
;             PG8_WAIT_V(8); PG8_WAIT_L(0); PG8_BAR; PG8_MMA(0, 0, At, B0); PG8_MMA(0, 1, At, B1); PG8_BAR; PG8_SCHED;
	s_add_i32 s76, 0, 0x18000
	s_add_i32 s77, 0, 0x1c000
	v_add_u32_e32 v156, s76, v141
	v_add_u32_e32 v163, s77, v141
	ds_read_b128 v[144:147], v156
	ds_read_b128 v[148:151], v156 offset:1024
	ds_read_b128 v[152:155], v156 offset:2048
	ds_read_b128 v[156:159], v156 offset:3072
	ds_read_b128 v[164:167], v163
	ds_read_b128 v[168:171], v163 offset:1024
	ds_read_b128 v[172:175], v163 offset:2048
	ds_read_b128 v[176:179], v163 offset:3072
	s_add_u32 s52, s52, 0x80000
	s_addc_u32 s53, s53, 0
	s_mov_b32 m0, s56
	v_lshl_add_u64 v[238:239], s[52:53], 0, v[132:133]
	ds_read_b128 v[180:183], v143 offset:32768
	ds_read_b128 v[184:187], v143 offset:33792
	ds_read_b128 v[188:191], v143 offset:34816
	ds_read_b128 v[192:195], v143 offset:35840
	ds_read_b128 v[196:199], v143 offset:36864
	ds_read_b128 v[222:225], v143 offset:37888
	ds_read_b128 v[226:229], v143 offset:38912
	ds_read_b128 v[230:233], v143 offset:39936
	global_load_lds_dwordx4 v[238:239], off
	v_lshl_add_u64 v[238:239], s[52:53], 0, v[130:131]
	s_mov_b32 m0, s57
	s_nop 0
	global_load_lds_dwordx4 v[238:239], off
	s_waitcnt vmcnt(8)
	s_waitcnt lgkmcnt(0)
	s_barrier
	s_setprio 1
	s_waitcnt lgkmcnt(0)
	v_mfma_f32_16x16x32_bf16 v[124:127], v[144:147], v[180:183], v[124:127]
	v_mfma_f32_16x16x32_bf16 v[116:119], v[152:155], v[180:183], v[116:119]
	v_mfma_f32_16x16x32_bf16 v[108:111], v[144:147], v[188:191], v[108:111]
	v_mfma_f32_16x16x32_bf16 v[100:103], v[152:155], v[188:191], v[100:103]
	v_mfma_f32_16x16x32_bf16 v[92:95], v[144:147], v[196:199], v[92:95]
	v_mfma_f32_16x16x32_bf16 v[84:87], v[152:155], v[196:199], v[84:87]
	v_mfma_f32_16x16x32_bf16 v[76:79], v[144:147], v[226:229], v[76:79]
	v_mfma_f32_16x16x32_bf16 v[68:71], v[152:155], v[226:229], v[68:71]
	v_mfma_f32_16x16x32_bf16 v[124:127], v[148:151], v[184:187], v[124:127]
	v_mfma_f32_16x16x32_bf16 v[116:119], v[156:159], v[184:187], v[116:119]
	v_mfma_f32_16x16x32_bf16 v[108:111], v[148:151], v[192:195], v[108:111]
	v_mfma_f32_16x16x32_bf16 v[100:103], v[156:159], v[192:195], v[100:103]
	v_mfma_f32_16x16x32_bf16 v[92:95], v[148:151], v[222:225], v[92:95]
	v_mfma_f32_16x16x32_bf16 v[84:87], v[156:159], v[222:225], v[84:87]
	v_mfma_f32_16x16x32_bf16 v[76:79], v[148:151], v[230:233], v[76:79]
	v_mfma_f32_16x16x32_bf16 v[68:71], v[156:159], v[230:233], v[68:71]
	s_setprio 0
	s_setprio 1
	v_mfma_f32_16x16x32_bf16 v[120:123], v[164:167], v[180:183], v[120:123]
	v_mfma_f32_16x16x32_bf16 v[112:115], v[172:175], v[180:183], v[112:115]
	v_mfma_f32_16x16x32_bf16 v[104:107], v[164:167], v[188:191], v[104:107]
	v_mfma_f32_16x16x32_bf16 v[96:99], v[172:175], v[188:191], v[96:99]
	v_mfma_f32_16x16x32_bf16 v[88:91], v[164:167], v[196:199], v[88:91]
	v_mfma_f32_16x16x32_bf16 v[80:83], v[172:175], v[196:199], v[80:83]
	v_mfma_f32_16x16x32_bf16 v[72:75], v[164:167], v[226:229], v[72:75]
	v_mfma_f32_16x16x32_bf16 v[64:67], v[172:175], v[226:229], v[64:67]
	v_mfma_f32_16x16x32_bf16 v[120:123], v[168:171], v[184:187], v[120:123]
	v_mfma_f32_16x16x32_bf16 v[112:115], v[176:179], v[184:187], v[112:115]
	v_mfma_f32_16x16x32_bf16 v[104:107], v[168:171], v[192:195], v[104:107]
	v_mfma_f32_16x16x32_bf16 v[96:99], v[176:179], v[192:195], v[96:99]
	v_mfma_f32_16x16x32_bf16 v[88:91], v[168:171], v[222:225], v[88:91]
	v_mfma_f32_16x16x32_bf16 v[80:83], v[176:179], v[222:225], v[80:83]
	v_mfma_f32_16x16x32_bf16 v[72:75], v[168:171], v[230:233], v[72:75]
	v_mfma_f32_16x16x32_bf16 v[64:67], v[176:179], v[230:233], v[64:67]
	s_setprio 0
	s_barrier
; #define PG8_STAGE(bufoff, gbase, voff) do { _Pragma("unroll") for (int _i = 0; _i < 2; ++_i) \
;         __builtin_amdgcn_global_load_lds((const unsigned*)((const char*)(gbase) + (voff)[_i]), (PG8_LAS unsigned*)(lds + (bufoff) + ldsw + _i * 8192), 16, 0, 0); } while (0)
; #define PG8_LDA(dst, b, h) do { _Pragma("unroll") for (int m = 0; m < 4; ++m) _Pragma("unroll") for (int k = 0; k < 2; ++k) dst[m][k] = *(const PG8_LAS bf16x8*)(lds + PG8_SA(b, h) + aoff + m * 2048 + k * 1024); } while (0)
; #define PG8_MMA(ai, bj, At, Bt) do { __builtin_amdgcn_s_setprio(1); _Pragma("unroll") for (int m = 0; m < 4; ++m) _Pragma("unroll") for (int n = 0; n < 2; ++n) _Pragma("unroll") for (int k = 0; k < 2; ++k) \
;         acc[ai][bj][m][n] = __builtin_amdgcn_mfma_f32_16x16x32_bf16(Bt[n][k], At[m][k], acc[ai][bj][m][n], 0, 0, 0); __builtin_amdgcn_s_setprio(0); } while (0)
; #define PG8_WAIT_V(n) asm volatile("s_waitcnt vmcnt(" #n ")" ::: "memory")
; #define PG8_WAIT_L(n) asm volatile("s_waitcnt lgkmcnt(" #n ")" ::: "memory")
; #define PG8_BAR __builtin_amdgcn_s_barrier()
; #define PG8_SCHED __builtin_amdgcn_sched_barrier(0)
; template <class Epi, class Sched, bool ALIGN_EPI = false, bool SP2 = false>
; __device__ __forceinline__ void gemm_phase(PG8_LAS unsigned char* lds, const Gemm g, const Sched& S, const Epi& E) {
;     ...
;         for (int t = 0; t < nt; t += 2) {
;             const bool last = (t == nt - 2);
;             const char* a1 = cA + (size_t)(t + 1) * kstep;
;             const char* a2 = last ? nA : cA + (size_t)(t + 2) * kstep; const char* b2 = last ? nB : cB + (size_t)(t + 2) * kstep;
;             const char* a3 = a2 + kstep; const char* b3 = b2 + kstep;
;             if (last && has_next) S.a_ready(nxt);
;     ...
;             PG8_LDA(At, 1, 1); PG8_STAGE(PG8_SB(1, 0), b3, voffB); PG8_STAGE(PG8_SB(1, 1), b3 + hstep, voffB); PG8_STAGE(PG8_SA(1, 0), a3, voffA);
;             PG8_WAIT_V(8); PG8_WAIT_L(0); PG8_BAR; PG8_MMA(1, 0, At, B0); PG8_MMA(1, 1, At, B1); PG8_BAR; PG8_SCHED;
;     ...
;         if constexpr (ALIGN_EPI) { if (wr == 0) PG8_BAR; }
	s_add_i32 s52, s76, s24
	v_lshl_add_u64 v[138:139], v[138:139], 0, s[30:31]
	s_mov_b32 m0, s52
	ds_read_b128 v[180:183], v143 offset:49152
	ds_read_b128 v[184:187], v143 offset:50176
	ds_read_b128 v[188:191], v143 offset:51200
	ds_read_b128 v[192:195], v143 offset:52224
	ds_read_b128 v[196:199], v143 offset:53248
	ds_read_b128 v[222:225], v143 offset:54272
	ds_read_b128 v[226:229], v143 offset:55296
	ds_read_b128 v[230:233], v143 offset:56320
	global_load_lds_dwordx4 v[138:139], off
	s_add_i32 m0, s52, 0x2000
	s_add_u32 s4, s4, 0x80080
	v_lshl_add_u64 v[138:139], v[200:201], 0, s[30:31]
	s_addc_u32 s5, s5, 0
	s_add_i32 s52, s77, s24
	global_load_lds_dwordx4 v[138:139], off
	v_lshl_add_u64 v[138:139], s[4:5], 0, v[160:161]
	s_mov_b32 m0, s52
	s_nop 0
	global_load_lds_dwordx4 v[138:139], off
	v_lshl_add_u64 v[138:139], s[4:5], 0, v[128:129]
	s_add_i32 m0, s52, 0x2000
	s_nop 0
	global_load_lds_dwordx4 v[138:139], off
	v_lshl_add_u64 v[138:139], v[234:235], 0, s[30:31]
	s_mov_b32 m0, s58
	s_nop 0
	global_load_lds_dwordx4 v[138:139], off
	v_lshl_add_u64 v[138:139], v[236:237], 0, s[30:31]
	s_mov_b32 m0, s59
	s_nop 0
	global_load_lds_dwordx4 v[138:139], off
	s_waitcnt vmcnt(8)
	s_waitcnt lgkmcnt(0)
	s_barrier
	s_setprio 1
	s_waitcnt lgkmcnt(0)
	v_mfma_f32_16x16x32_bf16 v[60:63], v[144:147], v[180:183], v[60:63]
	v_mfma_f32_16x16x32_bf16 v[52:55], v[152:155], v[180:183], v[52:55]
	v_mfma_f32_16x16x32_bf16 v[44:47], v[144:147], v[188:191], v[44:47]
	v_mfma_f32_16x16x32_bf16 v[36:39], v[152:155], v[188:191], v[36:39]
	v_mfma_f32_16x16x32_bf16 v[28:31], v[144:147], v[196:199], v[28:31]
	v_mfma_f32_16x16x32_bf16 v[20:23], v[152:155], v[196:199], v[20:23]
	v_mfma_f32_16x16x32_bf16 v[12:15], v[144:147], v[226:229], v[12:15]
	v_mfma_f32_16x16x32_bf16 v[4:7], v[152:155], v[226:229], v[4:7]
	v_mfma_f32_16x16x32_bf16 v[60:63], v[148:151], v[184:187], v[60:63]
	v_mfma_f32_16x16x32_bf16 v[52:55], v[156:159], v[184:187], v[52:55]
	v_mfma_f32_16x16x32_bf16 v[44:47], v[148:151], v[192:195], v[44:47]
	v_mfma_f32_16x16x32_bf16 v[36:39], v[156:159], v[192:195], v[36:39]
	v_mfma_f32_16x16x32_bf16 v[28:31], v[148:151], v[222:225], v[28:31]
	v_mfma_f32_16x16x32_bf16 v[20:23], v[156:159], v[222:225], v[20:23]
	v_mfma_f32_16x16x32_bf16 v[12:15], v[148:151], v[230:233], v[12:15]
	v_mfma_f32_16x16x32_bf16 v[4:7], v[156:159], v[230:233], v[4:7]
	s_setprio 0
	s_setprio 1
	v_mfma_f32_16x16x32_bf16 v[56:59], v[164:167], v[180:183], v[56:59]
	v_mfma_f32_16x16x32_bf16 v[48:51], v[172:175], v[180:183], v[48:51]
	v_mfma_f32_16x16x32_bf16 v[40:43], v[164:167], v[188:191], v[40:43]
	v_mfma_f32_16x16x32_bf16 v[32:35], v[172:175], v[188:191], v[32:35]
	v_mfma_f32_16x16x32_bf16 v[24:27], v[164:167], v[196:199], v[24:27]
	v_mfma_f32_16x16x32_bf16 v[16:19], v[172:175], v[196:199], v[16:19]
	v_mfma_f32_16x16x32_bf16 v[8:11], v[164:167], v[226:229], v[8:11]
	v_mfma_f32_16x16x32_bf16 v[0:3], v[172:175], v[226:229], v[0:3]
	v_mfma_f32_16x16x32_bf16 v[56:59], v[168:171], v[184:187], v[56:59]
	v_mfma_f32_16x16x32_bf16 v[48:51], v[176:179], v[184:187], v[48:51]
	v_mfma_f32_16x16x32_bf16 v[40:43], v[168:171], v[192:195], v[40:43]
	v_mfma_f32_16x16x32_bf16 v[32:35], v[176:179], v[192:195], v[32:35]
	v_mfma_f32_16x16x32_bf16 v[24:27], v[168:171], v[222:225], v[24:27]
	v_mfma_f32_16x16x32_bf16 v[16:19], v[176:179], v[222:225], v[16:19]
	v_mfma_f32_16x16x32_bf16 v[8:11], v[168:171], v[230:233], v[8:11]
	v_mfma_f32_16x16x32_bf16 v[0:3], v[176:179], v[230:233], v[0:3]
	s_setprio 0
	s_barrier
	s_add_i32 s75, s75, 2
	s_add_u32 s70, s70, 0x100
	s_addc_u32 s71, s71, 0
	s_add_u32 s73, s73, 0x100
	s_addc_u32 s74, s74, 0
	s_cmp_gt_u32 s75, 29
	s_cbranch_scc0 .LBB0_849
	s_and_b64 vcc, exec, s[8:9]
	s_cbranch_vccz .LBB0_852
	s_barrier
